# mout phase: LDS fragment reads of the MFMA blocks issued six ahead into rotating registers with counted lgkmcnt (was read, wait 0, mfma per fragment)
# speedup vs baseline: 1.0204x; 1.0033x over previous
; #define LAS __attribute__((address_space(3)))
; __device__ __forceinline__ unsigned cvt_pk_bf16(float lo, float hi) { unsigned r; asm volatile("v_cvt_pk_bf16_f32 %0, %1, %2" : "=v"(r) : "v"(lo), "v"(hi)); return r; }
; __device__ __forceinline__ void mout_phase(const Params& p, LAS unsigned char* lds) {
;     ...
;         {
;             f32x4 S[8];
; #pragma unroll
;             for (int nb = 0; nb < 8; ++nb) S[nb] = (f32x4){0.f, 0.f, 0.f, 0.f};
; #pragma unroll
;             for (int kk = 0; kk < 4; ++kk)
; #pragma unroll
;                 for (int nb = 0; nb < 8; ++nb) { const bf16x8 kf = *(const LAS bf16x8*)(T + (nb * 16 + fr) * 136 + kk * 32 + fq * 8);
;                     S[nb] = __builtin_amdgcn_mfma_f32_16x16x32_bf16(kf, qf[kk], S[nb], 0, 0, 0); }
;             const float rb = fv[j];
; #pragma unroll
;             for (int nb = 0; nb < 8; ++nb) { const int l0 = nb * 16 + 4 * fq; const f32x4 cw = *(const LAS f32x4*)(fv + 128 + l0);
;                 float sv[4];
; #pragma unroll
;                 for (int i = 0; i < 4; ++i) { const int l = l0 + i; const bool valid = dir ? (l >= j) : (l <= j); sv[i] = valid ? S[nb][i] * __expf(rb + cw[i]) : 0.f; }
;                 u32x2 o; o.x = cvt_pk_bf16(sv[0], sv[1]); o.y = cvt_pk_bf16(sv[2], sv[3]); *(LAS u32x2*)(sb + j * 136 + l0) = o; }
.LBB0_1496:
	s_or_b64 exec, exec, s[66:67]
	s_waitcnt lgkmcnt(0)
	s_barrier
	ds_read_b128 v[72:75], v201
	ds_read_b128 v[104:107], v201 offset:64
	ds_read_b128 v[76:79], v201 offset:4352
	ds_read_b128 v[80:83], v201 offset:8704
	ds_read_b128 v[84:87], v201 offset:13056
	ds_read_b128 v[88:91], v201 offset:17408
	s_waitcnt lgkmcnt(5)
	v_mfma_f32_16x16x32_bf16 v[72:75], v[72:75], v[16:19], 0
	ds_read_b128 v[92:95], v201 offset:21760
	ds_read_b128 v[96:99], v201 offset:26112
	ds_read_b128 v[100:103], v201 offset:30464
	s_waitcnt lgkmcnt(7)
	v_mfma_f32_16x16x32_bf16 v[72:75], v[104:107], v[20:23], v[72:75]
	ds_read_b128 v[104:107], v201 offset:4416
	s_cmp_lg_u32 s82, 0
	s_cselect_b64 s[80:81], -1, 0
	s_waitcnt lgkmcnt(7)
	v_mfma_f32_16x16x32_bf16 v[76:79], v[76:79], v[16:19], 0
	s_cmp_eq_u32 s82, 0
	s_cselect_b64 vcc, -1, 0
	v_readlane_b32 s36, v254, 38
	s_waitcnt lgkmcnt(0)
	v_mfma_f32_16x16x32_bf16 v[76:79], v[104:107], v[20:23], v[76:79]
	ds_read_b128 v[104:107], v201 offset:8768
	v_readlane_b32 s37, v254, 39
	v_mfma_f32_16x16x32_bf16 v[80:83], v[80:83], v[16:19], 0
	s_waitcnt lgkmcnt(0)
	v_mfma_f32_16x16x32_bf16 v[80:83], v[104:107], v[20:23], v[80:83]
	ds_read_b128 v[104:107], v201 offset:13120
	v_mfma_f32_16x16x32_bf16 v[84:87], v[84:87], v[16:19], 0
	s_waitcnt lgkmcnt(0)
	v_mfma_f32_16x16x32_bf16 v[84:87], v[104:107], v[20:23], v[84:87]
	ds_read_b128 v[104:107], v201 offset:17472
	v_mfma_f32_16x16x32_bf16 v[88:91], v[88:91], v[16:19], 0
	s_waitcnt lgkmcnt(0)
	v_mfma_f32_16x16x32_bf16 v[88:91], v[104:107], v[20:23], v[88:91]
	ds_read_b128 v[104:107], v201 offset:21824
	v_mfma_f32_16x16x32_bf16 v[92:95], v[92:95], v[16:19], 0
	s_waitcnt lgkmcnt(0)
	v_mfma_f32_16x16x32_bf16 v[92:95], v[104:107], v[20:23], v[92:95]
	ds_read_b128 v[104:107], v201 offset:26176
	v_mfma_f32_16x16x32_bf16 v[96:99], v[96:99], v[16:19], 0
	s_waitcnt lgkmcnt(0)
	v_mfma_f32_16x16x32_bf16 v[96:99], v[104:107], v[20:23], v[96:99]
	ds_read_b128 v[104:107], v201 offset:30528
	v_mfma_f32_16x16x32_bf16 v[100:103], v[100:103], v[16:19], 0
	s_waitcnt lgkmcnt(0)
	v_mfma_f32_16x16x32_bf16 v[100:103], v[104:107], v[20:23], v[100:103]
	ds_read_b128 v[228:231], v201 offset:128
	ds_read_b128 v[232:235], v201 offset:4480
	ds_read_b128 v[236:239], v201 offset:8832
	s_waitcnt lgkmcnt(2)
	v_mfma_f32_16x16x32_bf16 v[72:75], v[228:231], v[24:27], v[72:75]
	ds_read_b128 v[104:107], v201 offset:13184
	s_waitcnt lgkmcnt(2)
	v_mfma_f32_16x16x32_bf16 v[76:79], v[232:235], v[24:27], v[76:79]
	s_waitcnt lgkmcnt(1)
	v_mfma_f32_16x16x32_bf16 v[80:83], v[236:239], v[24:27], v[80:83]
	s_waitcnt lgkmcnt(0)
	v_mfma_f32_16x16x32_bf16 v[84:87], v[104:107], v[24:27], v[84:87]
	ds_read_b128 v[104:107], v201 offset:17536
	s_waitcnt lgkmcnt(0)
	v_mfma_f32_16x16x32_bf16 v[104:107], v[104:107], v[24:27], v[88:91]
	s_nop 2
	ds_read_b128 v[228:231], v201 offset:21888
	ds_read_b128 v[232:235], v201 offset:26240
	ds_read_b128 v[236:239], v201 offset:30592
	s_waitcnt lgkmcnt(2)
	v_mfma_f32_16x16x32_bf16 v[108:111], v[228:231], v[24:27], v[92:95]
	ds_read_b128 v[88:91], v201 offset:192
	s_waitcnt lgkmcnt(2)
	v_mfma_f32_16x16x32_bf16 v[112:115], v[232:235], v[24:27], v[96:99]
	s_waitcnt lgkmcnt(1)
	v_mfma_f32_16x16x32_bf16 v[116:119], v[236:239], v[24:27], v[100:103]
	s_waitcnt lgkmcnt(0)
	v_mfma_f32_16x16x32_bf16 v[100:103], v[88:91], v[28:31], v[72:75]
	s_nop 2
	ds_read_b128 v[228:231], v201 offset:4544
	ds_read_b128 v[232:235], v201 offset:8896
	ds_read_b128 v[236:239], v201 offset:13248
	s_waitcnt lgkmcnt(2)
	v_mfma_f32_16x16x32_bf16 v[96:99], v[228:231], v[28:31], v[76:79]
	ds_read_b128 v[72:75], v201 offset:17600
	s_waitcnt lgkmcnt(2)
	v_mfma_f32_16x16x32_bf16 v[92:95], v[232:235], v[28:31], v[80:83]
	s_waitcnt lgkmcnt(1)
	v_mfma_f32_16x16x32_bf16 v[88:91], v[236:239], v[28:31], v[84:87]
	s_waitcnt lgkmcnt(0)
	v_mfma_f32_16x16x32_bf16 v[84:87], v[72:75], v[28:31], v[104:107]
	ds_read_b128 v[72:75], v201 offset:21952
	s_nop 1
	ds_read_b32 v104, v195
	v_cndmask_b32_e64 v105, 0, 1, s[94:95]
	s_waitcnt lgkmcnt(1)
	v_mfma_f32_16x16x32_bf16 v[80:83], v[72:75], v[28:31], v[108:111]
	ds_read_b128 v[72:75], v201 offset:26304
	s_nop 1
	ds_read_b128 v[106:109], v202
	v_cndmask_b32_e64 v110, 0, 1, s[92:93]
	v_cndmask_b32_e32 v105, v110, v105, vcc
	v_and_b32_e32 v105, 1, v105
	v_cmp_eq_u32_e64 s[66:67], 1, v105
	s_waitcnt lgkmcnt(0)
	v_add_f32_e32 v105, v104, v106
	v_mul_f32_e32 v105, 0x3fb8aa3b, v105
	v_exp_f32_e32 v105, v105
	v_cndmask_b32_e64 v106, 0, 1, s[96:97]
	v_mfma_f32_16x16x32_bf16 v[76:79], v[72:75], v[28:31], v[112:115]
	ds_read_b128 v[72:75], v201 offset:30656
	v_mul_f32_e32 v100, v100, v105
	v_cndmask_b32_e64 v105, 0, 1, s[6:7]
	v_cndmask_b32_e32 v105, v106, v105, vcc
	v_and_b32_e32 v105, 1, v105
	v_cndmask_b32_e64 v100, 0, v100, s[66:67]
	v_cmp_eq_u32_e64 s[66:67], 1, v105
	v_add_f32_e32 v105, v104, v107
	v_mul_f32_e32 v105, 0x3fb8aa3b, v105
	v_exp_f32_e32 v105, v105
	v_cndmask_b32_e64 v106, 0, 1, s[8:9]
	s_waitcnt lgkmcnt(0)
	v_mfma_f32_16x16x32_bf16 v[72:75], v[72:75], v[28:31], v[116:119]
	v_mul_f32_e32 v101, v101, v105
	v_cndmask_b32_e64 v105, 0, 1, s[10:11]
	v_cndmask_b32_e32 v105, v106, v105, vcc
	v_and_b32_e32 v105, 1, v105
	v_cndmask_b32_e64 v101, 0, v101, s[66:67]
	v_cmp_eq_u32_e64 s[66:67], 1, v105
	v_add_f32_e32 v105, v104, v108
	v_mul_f32_e32 v105, 0x3fb8aa3b, v105
	v_exp_f32_e32 v105, v105
	v_cndmask_b32_e64 v106, 0, 1, s[12:13]
	v_cvt_pk_bf16_f32 v100, v100, v101
	v_mul_f32_e32 v102, v102, v105
	v_cndmask_b32_e64 v105, 0, 1, s[14:15]
	v_cndmask_b32_e32 v105, v106, v105, vcc
	v_and_b32_e32 v105, 1, v105
	v_cndmask_b32_e64 v102, 0, v102, s[66:67]
	v_cmp_eq_u32_e64 s[66:67], 1, v105
	v_add_f32_e32 v105, v104, v109
	v_mul_f32_e32 v105, 0x3fb8aa3b, v105
	v_exp_f32_e32 v105, v105
	v_cndmask_b32_e64 v106, 0, 1, s[16:17]
	v_mul_f32_e32 v103, v103, v105
	v_cndmask_b32_e64 v103, 0, v103, s[66:67]
	v_cvt_pk_bf16_f32 v101, v102, v103
	ds_write_b64 v203, v[100:101]
	ds_read_b128 v[100:103], v204
	v_cndmask_b32_e64 v105, 0, 1, s[22:23]
	v_cndmask_b32_e32 v105, v106, v105, vcc
	v_and_b32_e32 v105, 1, v105
	v_cmp_eq_u32_e64 s[66:67], 1, v105
	s_waitcnt lgkmcnt(0)
; #define LAS __attribute__((address_space(3)))
; __device__ __forceinline__ unsigned cvt_pk_bf16(float lo, float hi) { unsigned r; asm volatile("v_cvt_pk_bf16_f32 %0, %1, %2" : "=v"(r) : "v"(lo), "v"(hi)); return r; }
; __device__ __forceinline__ void mout_phase(const Params& p, LAS unsigned char* lds) {
;     ...
;             for (int nb = 0; nb < 8; ++nb) { const int l0 = nb * 16 + 4 * fq; const f32x4 cw = *(const LAS f32x4*)(fv + 128 + l0);
;                 float sv[4];
; #pragma unroll
;                 for (int i = 0; i < 4; ++i) { const int l = l0 + i; const bool valid = dir ? (l >= j) : (l <= j); sv[i] = valid ? S[nb][i] * __expf(rb + cw[i]) : 0.f; }
;                 u32x2 o; o.x = cvt_pk_bf16(sv[0], sv[1]); o.y = cvt_pk_bf16(sv[2], sv[3]); *(LAS u32x2*)(sb + j * 136 + l0) = o; }
	v_add_f32_e32 v100, v104, v100
	v_mul_f32_e32 v100, 0x3fb8aa3b, v100
	v_exp_f32_e32 v100, v100
	v_cndmask_b32_e64 v105, 0, 1, s[24:25]
	v_mul_f32_e32 v96, v96, v100
	v_cndmask_b32_e64 v100, 0, 1, s[26:27]
	v_cndmask_b32_e32 v100, v105, v100, vcc
	v_and_b32_e32 v100, 1, v100
	v_cndmask_b32_e64 v96, 0, v96, s[66:67]
	v_cmp_eq_u32_e64 s[66:67], 1, v100
	v_add_f32_e32 v100, v104, v101
	v_mul_f32_e32 v100, 0x3fb8aa3b, v100
	v_exp_f32_e32 v100, v100
	v_cndmask_b32_e64 v101, 0, 1, s[28:29]
	v_mul_f32_e32 v97, v97, v100
	v_cndmask_b32_e64 v100, 0, 1, s[30:31]
	v_cndmask_b32_e32 v100, v101, v100, vcc
	v_and_b32_e32 v100, 1, v100
	v_cndmask_b32_e64 v97, 0, v97, s[66:67]
	v_cmp_eq_u32_e64 s[66:67], 1, v100
	v_add_f32_e32 v100, v104, v102
	v_mul_f32_e32 v100, 0x3fb8aa3b, v100
	v_exp_f32_e32 v100, v100
	v_cndmask_b32_e64 v101, 0, 1, s[34:35]
	v_cvt_pk_bf16_f32 v96, v96, v97
	v_mul_f32_e32 v98, v98, v100
	v_cndmask_b32_e64 v100, 0, 1, s[36:37]
	v_cndmask_b32_e32 v100, v101, v100, vcc
	v_and_b32_e32 v100, 1, v100
	v_cndmask_b32_e64 v98, 0, v98, s[66:67]
	v_cmp_eq_u32_e64 s[66:67], 1, v100
	v_add_f32_e32 v100, v104, v103
	v_mul_f32_e32 v100, 0x3fb8aa3b, v100
	v_exp_f32_e32 v100, v100
	v_readlane_b32 s36, v254, 42
	v_readlane_b32 s37, v254, 43
	v_mul_f32_e32 v99, v99, v100
	v_cndmask_b32_e64 v99, 0, v99, s[66:67]
	v_cvt_pk_bf16_f32 v97, v98, v99
	ds_write_b64 v203, v[96:97] offset:32
	ds_read_b128 v[96:99], v205
	v_cndmask_b32_e64 v100, 0, 1, s[36:37]
	v_readlane_b32 s36, v254, 40
	v_readlane_b32 s37, v254, 41
	s_waitcnt lgkmcnt(0)
	v_add_f32_e32 v96, v104, v96
	v_mul_f32_e32 v96, 0x3fb8aa3b, v96
	v_exp_f32_e32 v96, v96
	v_cndmask_b32_e64 v101, 0, 1, s[36:37]
	v_readlane_b32 s36, v254, 46
	v_readlane_b32 s37, v254, 47
	v_cndmask_b32_e32 v100, v101, v100, vcc
	v_mul_f32_e32 v92, v92, v96
	v_cndmask_b32_e64 v96, 0, 1, s[36:37]
	v_readlane_b32 s36, v254, 44
	v_and_b32_e32 v100, 1, v100
	v_readlane_b32 s37, v254, 45
	v_cmp_eq_u32_e64 s[66:67], 1, v100
	s_nop 0
	v_cndmask_b32_e64 v100, 0, 1, s[36:37]
	v_cndmask_b32_e32 v96, v100, v96, vcc
	v_and_b32_e32 v96, 1, v96
	v_cndmask_b32_e64 v92, 0, v92, s[66:67]
	v_cmp_eq_u32_e64 s[66:67], 1, v96
	v_add_f32_e32 v96, v104, v97
	v_mul_f32_e32 v96, 0x3fb8aa3b, v96
	v_exp_f32_e32 v96, v96
	v_readlane_b32 s36, v254, 50
	v_readlane_b32 s37, v254, 51
	v_mul_f32_e32 v93, v93, v96
	s_nop 0
	v_cndmask_b32_e64 v96, 0, 1, s[36:37]
	v_readlane_b32 s36, v254, 48
	v_readlane_b32 s37, v254, 49
	v_cndmask_b32_e64 v93, 0, v93, s[66:67]
	v_cvt_pk_bf16_f32 v92, v92, v93
	s_nop 0
	v_cndmask_b32_e64 v97, 0, 1, s[36:37]
	v_cndmask_b32_e32 v96, v97, v96, vcc
	v_and_b32_e32 v96, 1, v96
	v_cmp_eq_u32_e64 s[66:67], 1, v96
	v_add_f32_e32 v96, v104, v98
	v_mul_f32_e32 v96, 0x3fb8aa3b, v96
	v_exp_f32_e32 v96, v96
	v_readlane_b32 s36, v254, 54
	v_readlane_b32 s37, v254, 55
	v_mul_f32_e32 v94, v94, v96
	s_nop 0
	v_cndmask_b32_e64 v96, 0, 1, s[36:37]
	v_readlane_b32 s36, v254, 52
	v_readlane_b32 s37, v254, 53
	v_cndmask_b32_e64 v94, 0, v94, s[66:67]
	s_nop 0
	v_cndmask_b32_e64 v97, 0, 1, s[36:37]
	v_cndmask_b32_e32 v96, v97, v96, vcc
	v_and_b32_e32 v96, 1, v96
	v_cmp_eq_u32_e64 s[66:67], 1, v96
	v_add_f32_e32 v96, v104, v99
	v_mul_f32_e32 v96, 0x3fb8aa3b, v96
	v_exp_f32_e32 v96, v96
	v_readlane_b32 s36, v254, 56
	v_readlane_b32 s37, v254, 57
	v_mul_f32_e32 v95, v95, v96
	v_cndmask_b32_e64 v95, 0, v95, s[66:67]
	v_cvt_pk_bf16_f32 v93, v94, v95
	ds_write_b64 v203, v[92:93] offset:64
	ds_read_b128 v[92:95], v206
	v_cndmask_b32_e64 v96, 0, 1, s[36:37]
	v_readlane_b32 s36, v254, 2
	v_readlane_b32 s37, v254, 3
	s_waitcnt lgkmcnt(0)
	v_add_f32_e32 v92, v104, v92
	v_mul_f32_e32 v92, 0x3fb8aa3b, v92
	v_exp_f32_e32 v92, v92
	v_cndmask_b32_e64 v97, 0, 1, s[36:37]
	v_readlane_b32 s36, v254, 60
	v_readlane_b32 s37, v254, 61
	v_cndmask_b32_e32 v96, v97, v96, vcc
	v_mul_f32_e32 v88, v88, v92
	v_cndmask_b32_e64 v92, 0, 1, s[36:37]
	v_readlane_b32 s36, v254, 58
	v_and_b32_e32 v96, 1, v96
	v_readlane_b32 s37, v254, 59
	v_cmp_eq_u32_e64 s[66:67], 1, v96
	s_nop 0
	v_cndmask_b32_e64 v96, 0, 1, s[36:37]
	v_cndmask_b32_e32 v92, v96, v92, vcc
	v_and_b32_e32 v92, 1, v92
	v_cndmask_b32_e64 v88, 0, v88, s[66:67]
	v_cmp_eq_u32_e64 s[66:67], 1, v92
	v_add_f32_e32 v92, v104, v93
	v_mul_f32_e32 v92, 0x3fb8aa3b, v92
	v_exp_f32_e32 v92, v92
	v_readlane_b32 s36, v255, 0
	v_readlane_b32 s37, v255, 1
	v_mul_f32_e32 v89, v89, v92
	s_nop 0
	v_cndmask_b32_e64 v92, 0, 1, s[36:37]
	v_readlane_b32 s36, v254, 62
	v_readlane_b32 s37, v254, 63
	v_cndmask_b32_e64 v89, 0, v89, s[66:67]
	v_cvt_pk_bf16_f32 v88, v88, v89
	s_nop 0
	v_cndmask_b32_e64 v93, 0, 1, s[36:37]
	v_cndmask_b32_e32 v92, v93, v92, vcc
	v_and_b32_e32 v92, 1, v92
	v_cmp_eq_u32_e64 s[66:67], 1, v92
	v_add_f32_e32 v92, v104, v94
	v_mul_f32_e32 v92, 0x3fb8aa3b, v92
	v_exp_f32_e32 v92, v92
	v_readlane_b32 s36, v255, 4
	v_readlane_b32 s37, v255, 5
	v_mul_f32_e32 v90, v90, v92
	s_nop 0
	v_cndmask_b32_e64 v92, 0, 1, s[36:37]
	v_readlane_b32 s36, v255, 2
	v_readlane_b32 s37, v255, 3
	v_cndmask_b32_e64 v90, 0, v90, s[66:67]
	s_nop 0
	v_cndmask_b32_e64 v93, 0, 1, s[36:37]
	v_cndmask_b32_e32 v92, v93, v92, vcc
	v_and_b32_e32 v92, 1, v92
	v_cmp_eq_u32_e64 s[66:67], 1, v92
	v_add_f32_e32 v92, v104, v95
	v_mul_f32_e32 v92, 0x3fb8aa3b, v92
	v_exp_f32_e32 v92, v92
	v_readlane_b32 s36, v255, 8
	v_readlane_b32 s37, v255, 9
	v_mul_f32_e32 v91, v91, v92
	v_cndmask_b32_e64 v91, 0, v91, s[66:67]
	v_cvt_pk_bf16_f32 v89, v90, v91
	ds_write_b64 v203, v[88:89] offset:96
	ds_read_b128 v[88:91], v207
	v_cndmask_b32_e64 v92, 0, 1, s[36:37]
	v_readlane_b32 s36, v255, 6
	v_readlane_b32 s37, v255, 7
	s_waitcnt lgkmcnt(0)
; #define LAS __attribute__((address_space(3)))
; __device__ __forceinline__ unsigned cvt_pk_bf16(float lo, float hi) { unsigned r; asm volatile("v_cvt_pk_bf16_f32 %0, %1, %2" : "=v"(r) : "v"(lo), "v"(hi)); return r; }
; __device__ __forceinline__ void mout_phase(const Params& p, LAS unsigned char* lds) {
;     ...
;             for (int nb = 0; nb < 8; ++nb) { const int l0 = nb * 16 + 4 * fq; const f32x4 cw = *(const LAS f32x4*)(fv + 128 + l0);
;                 float sv[4];
; #pragma unroll
;                 for (int i = 0; i < 4; ++i) { const int l = l0 + i; const bool valid = dir ? (l >= j) : (l <= j); sv[i] = valid ? S[nb][i] * __expf(rb + cw[i]) : 0.f; }
;                 u32x2 o; o.x = cvt_pk_bf16(sv[0], sv[1]); o.y = cvt_pk_bf16(sv[2], sv[3]); *(LAS u32x2*)(sb + j * 136 + l0) = o; }
;         }
;         __syncthreads();
	v_add_f32_e32 v88, v104, v88
	v_mul_f32_e32 v88, 0x3fb8aa3b, v88
	v_exp_f32_e32 v88, v88
	v_cndmask_b32_e64 v93, 0, 1, s[36:37]
	v_readlane_b32 s36, v255, 12
	v_readlane_b32 s37, v255, 13
	v_cndmask_b32_e32 v92, v93, v92, vcc
	v_mul_f32_e32 v84, v84, v88
	v_cndmask_b32_e64 v88, 0, 1, s[36:37]
	v_readlane_b32 s36, v255, 10
	v_and_b32_e32 v92, 1, v92
	v_readlane_b32 s37, v255, 11
	v_cmp_eq_u32_e64 s[66:67], 1, v92
	s_nop 0
	v_cndmask_b32_e64 v92, 0, 1, s[36:37]
	v_cndmask_b32_e32 v88, v92, v88, vcc
	v_and_b32_e32 v88, 1, v88
	v_cndmask_b32_e64 v84, 0, v84, s[66:67]
	v_cmp_eq_u32_e64 s[66:67], 1, v88
	v_add_f32_e32 v88, v104, v89
	v_mul_f32_e32 v88, 0x3fb8aa3b, v88
	v_exp_f32_e32 v88, v88
	v_readlane_b32 s36, v255, 16
	v_readlane_b32 s37, v255, 17
	v_mul_f32_e32 v85, v85, v88
	s_nop 0
	v_cndmask_b32_e64 v88, 0, 1, s[36:37]
	v_readlane_b32 s36, v255, 14
	v_readlane_b32 s37, v255, 15
	v_cndmask_b32_e64 v85, 0, v85, s[66:67]
	v_cvt_pk_bf16_f32 v84, v84, v85
	s_nop 0
	v_cndmask_b32_e64 v89, 0, 1, s[36:37]
	v_cndmask_b32_e32 v88, v89, v88, vcc
	v_and_b32_e32 v88, 1, v88
	v_cmp_eq_u32_e64 s[66:67], 1, v88
	v_add_f32_e32 v88, v104, v90
	v_mul_f32_e32 v88, 0x3fb8aa3b, v88
	v_exp_f32_e32 v88, v88
	v_readlane_b32 s36, v255, 20
	v_readlane_b32 s37, v255, 21
	v_mul_f32_e32 v86, v86, v88
	s_nop 0
	v_cndmask_b32_e64 v88, 0, 1, s[36:37]
	v_readlane_b32 s36, v255, 18
	v_readlane_b32 s37, v255, 19
	v_cndmask_b32_e64 v86, 0, v86, s[66:67]
	s_nop 0
	v_cndmask_b32_e64 v89, 0, 1, s[36:37]
	v_cndmask_b32_e32 v88, v89, v88, vcc
	v_and_b32_e32 v88, 1, v88
	v_cmp_eq_u32_e64 s[66:67], 1, v88
	v_add_f32_e32 v88, v104, v91
	v_mul_f32_e32 v88, 0x3fb8aa3b, v88
	v_exp_f32_e32 v88, v88
	v_readlane_b32 s36, v255, 24
	v_readlane_b32 s37, v255, 25
	v_mul_f32_e32 v87, v87, v88
	v_cndmask_b32_e64 v87, 0, v87, s[66:67]
	v_cvt_pk_bf16_f32 v85, v86, v87
	ds_write_b64 v203, v[84:85] offset:128
	ds_read_b128 v[84:87], v208
	v_cndmask_b32_e64 v88, 0, 1, s[36:37]
	v_readlane_b32 s36, v255, 22
	v_readlane_b32 s37, v255, 23
	s_waitcnt lgkmcnt(0)
	v_add_f32_e32 v84, v104, v84
	v_mul_f32_e32 v84, 0x3fb8aa3b, v84
	v_exp_f32_e32 v84, v84
	v_cndmask_b32_e64 v89, 0, 1, s[36:37]
	v_readlane_b32 s36, v255, 28
	v_readlane_b32 s37, v255, 29
	v_cndmask_b32_e32 v88, v89, v88, vcc
	v_mul_f32_e32 v80, v80, v84
	v_cndmask_b32_e64 v84, 0, 1, s[36:37]
	v_readlane_b32 s36, v255, 26
	v_and_b32_e32 v88, 1, v88
	v_readlane_b32 s37, v255, 27
	v_cmp_eq_u32_e64 s[66:67], 1, v88
	s_nop 0
	v_cndmask_b32_e64 v88, 0, 1, s[36:37]
	v_cndmask_b32_e32 v84, v88, v84, vcc
	v_and_b32_e32 v84, 1, v84
	v_cndmask_b32_e64 v80, 0, v80, s[66:67]
	v_cmp_eq_u32_e64 s[66:67], 1, v84
	v_add_f32_e32 v84, v104, v85
	v_mul_f32_e32 v84, 0x3fb8aa3b, v84
	v_exp_f32_e32 v84, v84
	v_readlane_b32 s36, v255, 54
	v_readlane_b32 s37, v255, 55
	v_mul_f32_e32 v81, v81, v84
	s_nop 0
	v_cndmask_b32_e64 v84, 0, 1, s[36:37]
	v_readlane_b32 s36, v255, 52
	v_readlane_b32 s37, v255, 53
	v_cndmask_b32_e64 v81, 0, v81, s[66:67]
	v_cvt_pk_bf16_f32 v80, v80, v81
	s_nop 0
	v_cndmask_b32_e64 v85, 0, 1, s[36:37]
	v_cndmask_b32_e32 v84, v85, v84, vcc
	v_and_b32_e32 v84, 1, v84
	v_cmp_eq_u32_e64 s[66:67], 1, v84
	v_add_f32_e32 v84, v104, v86
	v_mul_f32_e32 v84, 0x3fb8aa3b, v84
	v_exp_f32_e32 v84, v84
	v_readlane_b32 s36, v255, 58
	v_readlane_b32 s37, v255, 59
	v_mul_f32_e32 v82, v82, v84
	s_nop 0
	v_cndmask_b32_e64 v84, 0, 1, s[36:37]
	v_readlane_b32 s36, v255, 56
	v_readlane_b32 s37, v255, 57
	v_cndmask_b32_e64 v82, 0, v82, s[66:67]
	s_nop 0
	v_cndmask_b32_e64 v85, 0, 1, s[36:37]
	v_cndmask_b32_e32 v84, v85, v84, vcc
	v_and_b32_e32 v84, 1, v84
	v_cmp_eq_u32_e64 s[66:67], 1, v84
	v_add_f32_e32 v84, v104, v87
	v_mul_f32_e32 v84, 0x3fb8aa3b, v84
	v_exp_f32_e32 v84, v84
	v_readlane_b32 s36, v255, 62
	v_readlane_b32 s37, v255, 63
	v_mul_f32_e32 v83, v83, v84
	v_cndmask_b32_e64 v83, 0, v83, s[66:67]
	v_cvt_pk_bf16_f32 v81, v82, v83
	ds_write_b64 v203, v[80:81] offset:160
	ds_read_b128 v[80:83], v209
	v_cndmask_b32_e64 v84, 0, 1, s[36:37]
	v_readlane_b32 s36, v255, 60
	v_readlane_b32 s37, v255, 61
	s_waitcnt lgkmcnt(0)
	v_add_f32_e32 v80, v104, v80
	v_mul_f32_e32 v80, 0x3fb8aa3b, v80
	v_exp_f32_e32 v80, v80
	v_cndmask_b32_e64 v85, 0, 1, s[36:37]
	v_cndmask_b32_e32 v84, v85, v84, vcc
	v_and_b32_e32 v84, 1, v84
	v_cmp_eq_u32_e64 s[66:67], 1, v84
	v_mul_f32_e32 v76, v76, v80
	v_cndmask_b32_e64 v80, 0, 1, s[40:41]
	v_cndmask_b32_e64 v84, 0, 1, s[38:39]
	v_cndmask_b32_e32 v80, v84, v80, vcc
	v_and_b32_e32 v80, 1, v80
	v_cndmask_b32_e64 v76, 0, v76, s[66:67]
	v_cmp_eq_u32_e64 s[66:67], 1, v80
	v_add_f32_e32 v80, v104, v81
	v_mul_f32_e32 v80, 0x3fb8aa3b, v80
	v_exp_f32_e32 v80, v80
	v_cndmask_b32_e64 v81, 0, 1, s[42:43]
	v_mul_f32_e32 v77, v77, v80
	v_cndmask_b32_e64 v80, 0, 1, s[44:45]
	v_cndmask_b32_e32 v80, v81, v80, vcc
	v_and_b32_e32 v80, 1, v80
	v_cndmask_b32_e64 v77, 0, v77, s[66:67]
	v_cmp_eq_u32_e64 s[66:67], 1, v80
	v_add_f32_e32 v80, v104, v82
	v_mul_f32_e32 v80, 0x3fb8aa3b, v80
	v_exp_f32_e32 v80, v80
	v_cndmask_b32_e64 v81, 0, 1, s[46:47]
	v_cvt_pk_bf16_f32 v76, v76, v77
	v_mul_f32_e32 v78, v78, v80
	v_cndmask_b32_e64 v80, 0, 1, s[48:49]
	v_cndmask_b32_e32 v80, v81, v80, vcc
	v_and_b32_e32 v80, 1, v80
	v_cndmask_b32_e64 v78, 0, v78, s[66:67]
	v_cmp_eq_u32_e64 s[66:67], 1, v80
	v_add_f32_e32 v80, v104, v83
	v_mul_f32_e32 v80, 0x3fb8aa3b, v80
	v_exp_f32_e32 v80, v80
	v_cndmask_b32_e64 v81, 0, 1, s[50:51]
	v_mul_f32_e32 v79, v79, v80
	v_cndmask_b32_e64 v79, 0, v79, s[66:67]
	v_cvt_pk_bf16_f32 v77, v78, v79
	ds_write_b64 v203, v[76:77] offset:192
	ds_read_b128 v[76:79], v210
	v_cndmask_b32_e64 v80, 0, 1, s[52:53]
	v_cndmask_b32_e32 v80, v81, v80, vcc
	v_and_b32_e32 v80, 1, v80
	v_cmp_eq_u32_e64 s[66:67], 1, v80
	s_waitcnt lgkmcnt(0)
	v_add_f32_e32 v76, v104, v76
	v_mul_f32_e32 v76, 0x3fb8aa3b, v76
	v_exp_f32_e32 v76, v76
	v_cndmask_b32_e64 v80, 0, 1, s[54:55]
	v_mul_f32_e32 v72, v72, v76
	v_cndmask_b32_e64 v76, 0, 1, s[56:57]
	v_cndmask_b32_e32 v76, v80, v76, vcc
	v_and_b32_e32 v76, 1, v76
	v_cndmask_b32_e64 v72, 0, v72, s[66:67]
	v_cmp_eq_u32_e64 s[66:67], 1, v76
	v_add_f32_e32 v76, v104, v77
	v_mul_f32_e32 v76, 0x3fb8aa3b, v76
	v_exp_f32_e32 v76, v76
	v_cndmask_b32_e64 v77, 0, 1, s[58:59]
	v_mul_f32_e32 v73, v73, v76
	v_cndmask_b32_e64 v76, 0, 1, s[60:61]
	v_cndmask_b32_e32 v76, v77, v76, vcc
	v_and_b32_e32 v76, 1, v76
	v_cndmask_b32_e64 v73, 0, v73, s[66:67]
	v_cmp_eq_u32_e64 s[66:67], 1, v76
	v_add_f32_e32 v76, v104, v78
	v_mul_f32_e32 v76, 0x3fb8aa3b, v76
	v_exp_f32_e32 v76, v76
	v_cndmask_b32_e64 v77, 0, 1, s[62:63]
	v_cvt_pk_bf16_f32 v72, v72, v73
	v_mul_f32_e32 v74, v74, v76
	v_cndmask_b32_e64 v76, 0, 1, s[64:65]
	v_cndmask_b32_e32 v76, v77, v76, vcc
	v_and_b32_e32 v76, 1, v76
	v_cmp_eq_u32_e32 vcc, 1, v76
	v_add_f32_e32 v76, v104, v79
	v_mul_f32_e32 v76, 0x3fb8aa3b, v76
	v_exp_f32_e32 v76, v76
	v_cndmask_b32_e64 v74, 0, v74, s[66:67]
	v_mul_f32_e32 v75, v75, v76
	v_cndmask_b32_e32 v75, 0, v75, vcc
	v_cvt_pk_bf16_f32 v73, v74, v75
	ds_write_b64 v203, v[72:73] offset:224
	s_waitcnt lgkmcnt(0)
	s_barrier
; #define LAS __attribute__((address_space(3)))
; __device__ __forceinline__ void mout_phase(const Params& p, LAS unsigned char* lds) {
;     ...
;         for (int i = 0; i < 9; ++i) { const int idx = t + 512 * i; if (idx < 272 * 16) *(LAS u32x4*)(T + (idx >> 4) * 136 + (idx & 15) * 8) = creg[i]; }
	ds_write_b128 v153, v[36:39]
	ds_write_b128 v216, v[40:43]
	ds_write_b128 v217, v[48:51]
	ds_write_b128 v218, v[52:55]
	ds_write_b128 v220, v[56:59]
	ds_write_b128 v221, v[60:63]
	ds_write_b128 v222, v[64:67]
	s_and_saveexec_b64 s[66:67], s[18:19]
	s_cbranch_execz .LBB0_1498
	s_waitcnt vmcnt(0)
	ds_write_b128 v223, v[68:71]

; #define LAS __attribute__((address_space(3)))
; __device__ __forceinline__ void mout_phase(const Params& p, LAS unsigned char* lds) {
;     ...
;         u32x4 vreg[8];
;         { const bf16_t* vt = VT + (size_t)(ck * 4 + h) * 256 * 128;
; #pragma unroll
;           for (int i = 0; i < 8; ++i) { const int idx = t + 512 * i; vreg[i] = *(const u32x4*)(vt + (size_t)(idx >> 4) * 128 + (idx & 15) * 8); } }
;         __syncthreads();
;         f32x4 acc[17];
; #pragma unroll
;         for (int nb = 0; nb < 17; ++nb) acc[nb] = (f32x4){0.f, 0.f, 0.f, 0.f};
; #pragma unroll
;         for (int kk = 0; kk < 4; ++kk)
; #pragma unroll
;             for (int nb = 0; nb < 17; ++nb) { const bf16x8 cf = *(const LAS bf16x8*)(T + (nb * 16 + fr) * 136 + kk * 32 + fq * 8);
;                 acc[nb] = __builtin_amdgcn_mfma_f32_16x16x32_bf16(cf, qf[kk], acc[nb], 0, 0, 0); }
.LBB0_1500:
	s_or_b64 exec, exec, s[66:67]
	s_ashr_i32 s66, s33, 3
	s_andn2_b32 s66, s66, 31
	s_or_b32 s85, s66, s70
	s_bfe_u32 s84, s33, 0x20006
	s_lshl_b32 s66, s85, 2
	s_or_b32 s66, s66, s84
	s_ashr_i32 s67, s66, 31
	s_lshl_b64 s[66:67], s[66:67], 16
	v_lshl_add_u64 v[36:37], v[144:145], 0, s[66:67]
	v_mov_b32_e32 v169, v139
	v_lshl_add_u64 v[38:39], v[36:37], 0, v[138:139]
	v_lshl_add_u64 v[40:41], v[36:37], 0, v[168:169]
	s_movk_i32 s66, 0x4000
	global_load_dwordx4 v[100:103], v[40:41], off
	v_add_co_u32_e32 v40, vcc, s66, v38
	v_mov_b32_e32 v171, v139
	s_nop 0
	v_addc_co_u32_e32 v41, vcc, 0, v39, vcc
	global_load_dwordx4 v[104:107], v[40:41], off
	v_lshl_add_u64 v[40:41], v[36:37], 0, v[170:171]
	s_mov_b32 s66, 0x8000
	global_load_dwordx4 v[112:115], v[40:41], off
	v_add_co_u32_e32 v40, vcc, s66, v38
	v_mov_b32_e32 v173, v139
	s_nop 0
	v_addc_co_u32_e32 v41, vcc, 0, v39, vcc
	v_mov_b32_e32 v175, v139
	global_load_dwordx4 v[108:111], v[40:41], off
	v_lshl_add_u64 v[40:41], v[36:37], 0, v[172:173]
	s_mov_b32 s66, 0xc000
	v_lshl_add_u64 v[36:37], v[36:37], 0, v[174:175]
	global_load_dwordx4 v[96:99], v[38:39], off
	global_load_dwordx4 v[124:127], v[36:37], off
	v_add_co_u32_e32 v38, vcc, s66, v38
	global_load_dwordx4 v[116:119], v[40:41], off
	s_nop 0
	v_addc_co_u32_e32 v39, vcc, 0, v39, vcc
	global_load_dwordx4 v[120:123], v[38:39], off
	s_waitcnt lgkmcnt(0)
	s_barrier
	ds_read_b128 v[36:39], v201
	ds_read_b128 v[178:181], v201 offset:64
	s_waitcnt lgkmcnt(1)
	v_mfma_f32_16x16x32_bf16 v[36:39], v[36:39], v[16:19], 0
	ds_read_b128 v[40:43], v201 offset:4352
	s_waitcnt vmcnt(8)
	ds_read_b128 v[44:47], v201 offset:8704
	ds_read_b128 v[48:51], v201 offset:13056
	s_waitcnt lgkmcnt(3)
	v_mfma_f32_16x16x32_bf16 v[36:39], v[178:181], v[20:23], v[36:39]
	ds_read_b128 v[178:181], v201 offset:4416
	ds_read_b128 v[52:55], v201 offset:17408
	ds_read_b128 v[56:59], v201 offset:21760
	s_waitcnt lgkmcnt(5)
	v_mfma_f32_16x16x32_bf16 v[40:43], v[40:43], v[16:19], 0
	ds_read_b128 v[60:63], v201 offset:26112
	ds_read_b128 v[64:67], v201 offset:30464
	ds_read_b128 v[68:71], v201 offset:34816
	ds_read_b32 v138, v195 offset:1024
	s_waitcnt lgkmcnt(6)
	v_mfma_f32_16x16x32_bf16 v[40:43], v[178:181], v[20:23], v[40:43]
	ds_read_b128 v[178:181], v201 offset:8768
	ds_read_b128 v[72:75], v201 offset:39168
	ds_read_b128 v[76:79], v201 offset:43520
	v_mfma_f32_16x16x32_bf16 v[44:47], v[44:47], v[16:19], 0
	ds_read_b128 v[80:83], v201 offset:47872
	ds_read_b128 v[84:87], v201 offset:52224
	ds_read_b128 v[88:91], v201 offset:56576
	s_waitcnt lgkmcnt(5)
	v_mfma_f32_16x16x32_bf16 v[44:47], v[178:181], v[20:23], v[44:47]
	ds_read_b128 v[178:181], v201 offset:13120
	ds_read_b128 v[92:95], v201 offset:60928
	ds_read_b128 v[128:131], v201 offset:65280
	v_mfma_f32_16x16x32_bf16 v[48:51], v[48:51], v[16:19], 0
	ds_read_b128 v[132:135], v212
	s_waitcnt lgkmcnt(3)
	v_mfma_f32_16x16x32_bf16 v[48:51], v[178:181], v[20:23], v[48:51]
	ds_read_b128 v[178:181], v201 offset:17472
	v_mfma_f32_16x16x32_bf16 v[52:55], v[52:55], v[16:19], 0
	s_waitcnt lgkmcnt(0)
	v_mfma_f32_16x16x32_bf16 v[52:55], v[178:181], v[20:23], v[52:55]
	ds_read_b128 v[178:181], v201 offset:21824
	v_mfma_f32_16x16x32_bf16 v[56:59], v[56:59], v[16:19], 0
	s_waitcnt lgkmcnt(0)
	v_mfma_f32_16x16x32_bf16 v[56:59], v[178:181], v[20:23], v[56:59]
	ds_read_b128 v[178:181], v201 offset:26176
	v_mfma_f32_16x16x32_bf16 v[60:63], v[60:63], v[16:19], 0
	s_waitcnt lgkmcnt(0)
	v_mfma_f32_16x16x32_bf16 v[60:63], v[178:181], v[20:23], v[60:63]
	ds_read_b128 v[178:181], v201 offset:30528
	v_mfma_f32_16x16x32_bf16 v[64:67], v[64:67], v[16:19], 0
	s_waitcnt lgkmcnt(0)
	v_mfma_f32_16x16x32_bf16 v[64:67], v[178:181], v[20:23], v[64:67]
	ds_read_b128 v[178:181], v201 offset:34880
	v_mfma_f32_16x16x32_bf16 v[68:71], v[68:71], v[16:19], 0
	s_waitcnt lgkmcnt(0)
	v_mfma_f32_16x16x32_bf16 v[68:71], v[178:181], v[20:23], v[68:71]
	ds_read_b128 v[178:181], v201 offset:39232
	v_mfma_f32_16x16x32_bf16 v[72:75], v[72:75], v[16:19], 0
	s_waitcnt lgkmcnt(0)
	v_mfma_f32_16x16x32_bf16 v[72:75], v[178:181], v[20:23], v[72:75]
	ds_read_b128 v[178:181], v201 offset:43584
	v_mfma_f32_16x16x32_bf16 v[76:79], v[76:79], v[16:19], 0
	s_waitcnt lgkmcnt(0)
	v_mfma_f32_16x16x32_bf16 v[76:79], v[178:181], v[20:23], v[76:79]
	ds_read_b128 v[178:181], v201 offset:47936
	v_mfma_f32_16x16x32_bf16 v[80:83], v[80:83], v[16:19], 0
	s_waitcnt lgkmcnt(0)
	v_mfma_f32_16x16x32_bf16 v[80:83], v[178:181], v[20:23], v[80:83]
	ds_read_b128 v[178:181], v201 offset:52288
	v_mfma_f32_16x16x32_bf16 v[84:87], v[84:87], v[16:19], 0
	s_waitcnt lgkmcnt(0)
	v_mfma_f32_16x16x32_bf16 v[84:87], v[178:181], v[20:23], v[84:87]
	ds_read_b128 v[178:181], v201 offset:56640
	v_mfma_f32_16x16x32_bf16 v[88:91], v[88:91], v[16:19], 0
	s_waitcnt lgkmcnt(0)
	v_mfma_f32_16x16x32_bf16 v[88:91], v[178:181], v[20:23], v[88:91]
	ds_read_b128 v[178:181], v201 offset:60992
	v_mfma_f32_16x16x32_bf16 v[92:95], v[92:95], v[16:19], 0
	s_waitcnt lgkmcnt(0)
	v_mfma_f32_16x16x32_bf16 v[92:95], v[178:181], v[20:23], v[92:95]
	ds_read_b128 v[178:181], v201 offset:65344
	v_mfma_f32_16x16x32_bf16 v[128:131], v[128:131], v[16:19], 0
	s_waitcnt lgkmcnt(0)
	v_mfma_f32_16x16x32_bf16 v[128:131], v[178:181], v[20:23], v[128:131]
	ds_read_b128 v[178:181], v212 offset:64
	v_mfma_f32_16x16x32_bf16 v[132:135], v[132:135], v[16:19], 0
	s_waitcnt lgkmcnt(0)
; #define LAS __attribute__((address_space(3)))
; __device__ __forceinline__ void mout_phase(const Params& p, LAS unsigned char* lds) {
;     ...
; #pragma unroll
;         for (int kk = 0; kk < 4; ++kk)
; #pragma unroll
;             for (int nb = 0; nb < 17; ++nb) { const bf16x8 cf = *(const LAS bf16x8*)(T + (nb * 16 + fr) * 136 + kk * 32 + fq * 8);
;                 acc[nb] = __builtin_amdgcn_mfma_f32_16x16x32_bf16(cf, qf[kk], acc[nb], 0, 0, 0); }
;         { const float aj = fv[256 + j];
; #pragma unroll
;           for (int nb = 0; nb < 17; ++nb) acc[nb] = acc[nb] * aj; }
;         __syncthreads();
; #pragma unroll
;         for (int i = 0; i < 8; ++i) { const int idx = t + 512 * i; *(LAS u32x4*)(T + (idx >> 4) * 136 + (idx & 15) * 8) = vreg[i]; }
;         if (t < 256) { const int r = 256 + (t >> 4), c8 = (t & 15) * 8; const unsigned one = (r == 256) ? 0x3F803F80u : 0u; *(LAS u32x4*)(T + r * 136 + c8) = (u32x4){one, one, one, one}; }
;         const float einv = fv[384 + j];
;         { const int un = (u & 1) ? u - 1 + 2 * (int)gridDim.x : u + 1; if (un < 2048) mout_issue(p, un, kreg, qf, gg); }
	v_mfma_f32_16x16x32_bf16 v[132:135], v[178:181], v[20:23], v[132:135]
	ds_read_b128 v[228:231], v201 offset:128
	ds_read_b128 v[232:235], v201 offset:4480
	ds_read_b128 v[236:239], v201 offset:8832
	ds_read_b128 v[240:243], v201 offset:13184
	ds_read_b128 v[246:249], v201 offset:17536
	ds_read_b128 v[250:253], v201 offset:21888
	s_waitcnt lgkmcnt(5)
	v_mfma_f32_16x16x32_bf16 v[36:39], v[228:231], v[24:27], v[36:39]
	ds_read_b128 v[228:231], v201 offset:26240
	s_waitcnt lgkmcnt(5)
	v_mfma_f32_16x16x32_bf16 v[40:43], v[232:235], v[24:27], v[40:43]
	ds_read_b128 v[232:235], v201 offset:30592
	s_waitcnt lgkmcnt(5)
	v_mfma_f32_16x16x32_bf16 v[44:47], v[236:239], v[24:27], v[44:47]
	ds_read_b128 v[236:239], v201 offset:34944
	s_waitcnt lgkmcnt(5)
	v_mfma_f32_16x16x32_bf16 v[48:51], v[240:243], v[24:27], v[48:51]
	ds_read_b128 v[240:243], v201 offset:39296
	s_waitcnt lgkmcnt(5)
	v_mfma_f32_16x16x32_bf16 v[52:55], v[246:249], v[24:27], v[52:55]
	ds_read_b128 v[246:249], v201 offset:43648
	s_waitcnt lgkmcnt(5)
	v_mfma_f32_16x16x32_bf16 v[56:59], v[250:253], v[24:27], v[56:59]
	ds_read_b128 v[250:253], v201 offset:48000
	s_waitcnt lgkmcnt(5)
	v_mfma_f32_16x16x32_bf16 v[60:63], v[228:231], v[24:27], v[60:63]
	ds_read_b128 v[228:231], v201 offset:52352
	s_waitcnt lgkmcnt(5)
	v_mfma_f32_16x16x32_bf16 v[64:67], v[232:235], v[24:27], v[64:67]
	ds_read_b128 v[232:235], v201 offset:56704
	s_waitcnt lgkmcnt(5)
	v_mfma_f32_16x16x32_bf16 v[68:71], v[236:239], v[24:27], v[68:71]
	ds_read_b128 v[236:239], v201 offset:61056
	s_waitcnt lgkmcnt(5)
	v_mfma_f32_16x16x32_bf16 v[72:75], v[240:243], v[24:27], v[72:75]
	ds_read_b128 v[240:243], v201 offset:65408
	s_waitcnt lgkmcnt(5)
	v_mfma_f32_16x16x32_bf16 v[76:79], v[246:249], v[24:27], v[76:79]
	ds_read_b128 v[246:249], v212 offset:128
	s_waitcnt lgkmcnt(5)
	v_mfma_f32_16x16x32_bf16 v[80:83], v[250:253], v[24:27], v[80:83]
	ds_read_b128 v[250:253], v201 offset:192
	s_waitcnt lgkmcnt(5)
	v_mfma_f32_16x16x32_bf16 v[84:87], v[228:231], v[24:27], v[84:87]
	ds_read_b128 v[228:231], v201 offset:4544
	s_waitcnt lgkmcnt(5)
	v_mfma_f32_16x16x32_bf16 v[88:91], v[232:235], v[24:27], v[88:91]
	ds_read_b128 v[232:235], v201 offset:8896
	s_waitcnt lgkmcnt(5)
	v_mfma_f32_16x16x32_bf16 v[92:95], v[236:239], v[24:27], v[92:95]
	ds_read_b128 v[236:239], v201 offset:13248
	s_waitcnt lgkmcnt(5)
	v_mfma_f32_16x16x32_bf16 v[128:131], v[240:243], v[24:27], v[128:131]
	ds_read_b128 v[240:243], v201 offset:17600
	s_waitcnt lgkmcnt(5)
	v_mfma_f32_16x16x32_bf16 v[132:135], v[246:249], v[24:27], v[132:135]
	ds_read_b128 v[246:249], v201 offset:21952
	s_waitcnt lgkmcnt(5)
	v_mfma_f32_16x16x32_bf16 v[36:39], v[250:253], v[28:31], v[36:39]
	ds_read_b128 v[250:253], v201 offset:26304
	s_waitcnt lgkmcnt(5)
	v_mfma_f32_16x16x32_bf16 v[40:43], v[228:231], v[28:31], v[40:43]
	ds_read_b128 v[228:231], v201 offset:30656
	s_waitcnt lgkmcnt(5)
	v_mfma_f32_16x16x32_bf16 v[44:47], v[232:235], v[28:31], v[44:47]
	ds_read_b128 v[232:235], v201 offset:35008
	s_waitcnt lgkmcnt(5)
	v_mfma_f32_16x16x32_bf16 v[48:51], v[236:239], v[28:31], v[48:51]
	ds_read_b128 v[236:239], v201 offset:39360
	s_waitcnt lgkmcnt(5)
	v_mfma_f32_16x16x32_bf16 v[52:55], v[240:243], v[28:31], v[52:55]
	ds_read_b128 v[240:243], v201 offset:43712
	s_waitcnt lgkmcnt(5)
	v_mfma_f32_16x16x32_bf16 v[56:59], v[246:249], v[28:31], v[56:59]
	ds_read_b128 v[246:249], v201 offset:48064
	s_waitcnt lgkmcnt(5)
	v_mfma_f32_16x16x32_bf16 v[60:63], v[250:253], v[28:31], v[60:63]
	ds_read_b128 v[250:253], v201 offset:52416
	s_waitcnt lgkmcnt(5)
	v_mfma_f32_16x16x32_bf16 v[64:67], v[228:231], v[28:31], v[64:67]
	ds_read_b128 v[228:231], v201 offset:56768
	s_waitcnt lgkmcnt(5)
	v_mfma_f32_16x16x32_bf16 v[68:71], v[232:235], v[28:31], v[68:71]
	ds_read_b128 v[232:235], v201 offset:61120
	s_waitcnt lgkmcnt(5)
	v_mfma_f32_16x16x32_bf16 v[72:75], v[236:239], v[28:31], v[72:75]
	ds_read_b128 v[178:181], v201 offset:65472
	s_waitcnt lgkmcnt(5)
	v_mfma_f32_16x16x32_bf16 v[76:79], v[240:243], v[28:31], v[76:79]
	s_waitcnt lgkmcnt(4)
	v_mfma_f32_16x16x32_bf16 v[80:83], v[246:249], v[28:31], v[80:83]
	s_waitcnt lgkmcnt(3)
	v_mfma_f32_16x16x32_bf16 v[84:87], v[250:253], v[28:31], v[84:87]
	s_waitcnt lgkmcnt(2)
	v_mfma_f32_16x16x32_bf16 v[88:91], v[228:231], v[28:31], v[88:91]
	s_waitcnt lgkmcnt(1)
	v_mfma_f32_16x16x32_bf16 v[92:95], v[232:235], v[28:31], v[92:95]
	s_waitcnt lgkmcnt(0)
	v_mfma_f32_16x16x32_bf16 v[128:131], v[178:181], v[28:31], v[128:131]
	ds_read_b128 v[178:181], v212 offset:192
	s_waitcnt lgkmcnt(0)
	s_barrier
	v_mfma_f32_16x16x32_bf16 v[132:135], v[178:181], v[28:31], v[132:135]
	s_waitcnt vmcnt(3)
	ds_write_b128 v153, v[96:99]
	ds_write_b128 v216, v[100:103]
	ds_write_b128 v217, v[104:107]
	ds_write_b128 v218, v[112:115]
	ds_write_b128 v220, v[108:111]
	s_waitcnt vmcnt(1)
	ds_write_b128 v221, v[116:119]
	s_waitcnt vmcnt(0)
	ds_write_b128 v222, v[120:123]
	ds_write_b128 v223, v[124:127]
	s_and_saveexec_b64 s[66:67], s[90:91]
	ds_write_b128 v197, v[32:35]
	s_or_b64 exec, exec, s[66:67]
	ds_read_b32 v153, v195 offset:1536
	v_cndmask_b32_e64 v96, 0, 1, s[80:81]
	v_cmp_ne_u32_e64 s[66:67], 1, v96
	s_andn2_b64 vcc, exec, s[80:81]
	s_mov_b64 s[80:81], -1
	s_cbranch_vccz .LBB0_1505
	s_andn2_b64 vcc, exec, s[80:81]
	s_cbranch_vccz .LBB0_1506

; #define LAS __attribute__((address_space(3)))
; __device__ __forceinline__ void mout_phase(const Params& p, LAS unsigned char* lds) {
;     ...
;         { const float aj = fv[256 + j];
; #pragma unroll
;           for (int nb = 0; nb < 17; ++nb) acc[nb] = acc[nb] * aj; }
;         __syncthreads();
; #pragma unroll
;         for (int i = 0; i < 8; ++i) { const int idx = t + 512 * i; *(LAS u32x4*)(T + (idx >> 4) * 136 + (idx & 15) * 8) = vreg[i]; }
;         if (t < 256) { const int r = 256 + (t >> 4), c8 = (t & 15) * 8; const unsigned one = (r == 256) ? 0x3F803F80u : 0u; *(LAS u32x4*)(T + r * 136 + c8) = (u32x4){one, one, one, one}; }
;         const float einv = fv[384 + j];
;         { const int un = (u & 1) ? u - 1 + 2 * (int)gridDim.x : u + 1; if (un < 2048) mout_issue(p, un, kreg, qf, gg); }
;         __syncthreads();
; #pragma unroll
;         for (int kk = 0; kk < 4; ++kk) { const bf16x8 sf = *(const LAS bf16x8*)(sb + j * 136 + kk * 32 + fq * 8);
; #pragma unroll
;             for (int nb = 0; nb < 17; ++nb) { const bf16x8 vf = *(const LAS bf16x8*)(T + (nb * 16 + fr) * 136 + kk * 32 + fq * 8);
;                 acc[nb] = __builtin_amdgcn_mfma_f32_16x16x32_bf16(vf, sf, acc[nb], 0, 0, 0); } }
.LBB0_1510:
	v_pk_mul_f32 v[102:103], v[62:63], v[138:139] op_sel_hi:[1,0]
	v_pk_mul_f32 v[100:101], v[60:61], v[138:139] op_sel_hi:[1,0]
	v_pk_mul_f32 v[98:99], v[66:67], v[138:139] op_sel_hi:[1,0]
	v_pk_mul_f32 v[96:97], v[64:65], v[138:139] op_sel_hi:[1,0]
	v_pk_mul_f32 v[66:67], v[74:75], v[138:139] op_sel_hi:[1,0]
	v_pk_mul_f32 v[64:65], v[72:73], v[138:139] op_sel_hi:[1,0]
	v_pk_mul_f32 v[62:63], v[78:79], v[138:139] op_sel_hi:[1,0]
	v_pk_mul_f32 v[60:61], v[76:77], v[138:139] op_sel_hi:[1,0]
	s_waitcnt lgkmcnt(0)
	s_barrier
	ds_read_b128 v[76:79], v200
	ds_read_b128 v[72:75], v201
	v_pk_mul_f32 v[126:127], v[38:39], v[138:139] op_sel_hi:[1,0]
	v_pk_mul_f32 v[124:125], v[36:37], v[138:139] op_sel_hi:[1,0]
	v_pk_mul_f32 v[114:115], v[50:51], v[138:139] op_sel_hi:[1,0]
	v_pk_mul_f32 v[112:113], v[48:49], v[138:139] op_sel_hi:[1,0]
	v_pk_mul_f32 v[50:51], v[90:91], v[138:139] op_sel_hi:[1,0]
	v_pk_mul_f32 v[48:49], v[88:89], v[138:139] op_sel_hi:[1,0]
	s_waitcnt lgkmcnt(0)
	v_mfma_f32_16x16x32_bf16 v[88:91], v[72:75], v[76:79], v[124:127]
	ds_read_b128 v[72:75], v201 offset:4352
	v_pk_mul_f32 v[122:123], v[42:43], v[138:139] op_sel_hi:[1,0]
	v_pk_mul_f32 v[120:121], v[40:41], v[138:139] op_sel_hi:[1,0]
	v_pk_mul_f32 v[118:119], v[46:47], v[138:139] op_sel_hi:[1,0]
	v_pk_mul_f32 v[116:117], v[44:45], v[138:139] op_sel_hi:[1,0]
	s_waitcnt lgkmcnt(0)
	v_mfma_f32_16x16x32_bf16 v[120:123], v[72:75], v[76:79], v[120:123]
	ds_read_b128 v[72:75], v201 offset:8704
	v_pk_mul_f32 v[110:111], v[54:55], v[138:139] op_sel_hi:[1,0]
	v_pk_mul_f32 v[108:109], v[52:53], v[138:139] op_sel_hi:[1,0]
	s_waitcnt lgkmcnt(0)
	v_mfma_f32_16x16x32_bf16 v[116:119], v[72:75], v[76:79], v[116:119]
	ds_read_b128 v[72:75], v201 offset:13056
	v_pk_mul_f32 v[106:107], v[58:59], v[138:139] op_sel_hi:[1,0]
	v_pk_mul_f32 v[104:105], v[56:57], v[138:139] op_sel_hi:[1,0]
	s_waitcnt lgkmcnt(0)
	v_mfma_f32_16x16x32_bf16 v[112:115], v[72:75], v[76:79], v[112:115]
	ds_read_b128 v[72:75], v201 offset:17408
	v_pk_mul_f32 v[46:47], v[94:95], v[138:139] op_sel_hi:[1,0]
	v_pk_mul_f32 v[44:45], v[92:93], v[138:139] op_sel_hi:[1,0]
	s_waitcnt lgkmcnt(0)
	v_mfma_f32_16x16x32_bf16 v[108:111], v[72:75], v[76:79], v[108:111]
	ds_read_b128 v[72:75], v201 offset:21760
	v_pk_mul_f32 v[58:59], v[82:83], v[138:139] op_sel_hi:[1,0]
	v_pk_mul_f32 v[56:57], v[80:81], v[138:139] op_sel_hi:[1,0]
	s_waitcnt lgkmcnt(0)
	v_mfma_f32_16x16x32_bf16 v[104:107], v[72:75], v[76:79], v[104:107]
	ds_read_b128 v[72:75], v201 offset:26112
	v_pk_mul_f32 v[70:71], v[70:71], v[138:139] op_sel_hi:[1,0]
	v_pk_mul_f32 v[68:69], v[68:69], v[138:139] op_sel_hi:[1,0]
	s_waitcnt lgkmcnt(0)
	v_mfma_f32_16x16x32_bf16 v[92:95], v[72:75], v[76:79], v[100:103]
	ds_read_b128 v[72:75], v201 offset:30464
	v_pk_mul_f32 v[54:55], v[86:87], v[138:139] op_sel_hi:[1,0]
	v_pk_mul_f32 v[52:53], v[84:85], v[138:139] op_sel_hi:[1,0]
	s_waitcnt lgkmcnt(0)
	v_mfma_f32_16x16x32_bf16 v[80:83], v[72:75], v[76:79], v[96:99]
	ds_read_b128 v[72:75], v201 offset:34816
	v_pk_mul_f32 v[42:43], v[130:131], v[138:139] op_sel_hi:[1,0]
	v_pk_mul_f32 v[40:41], v[128:129], v[138:139] op_sel_hi:[1,0]
	s_waitcnt lgkmcnt(0)
	v_mfma_f32_16x16x32_bf16 v[72:75], v[72:75], v[76:79], v[68:71]
	s_nop 2
	ds_read_b128 v[68:71], v201 offset:39168
	v_pk_mul_f32 v[38:39], v[134:135], v[138:139] op_sel_hi:[1,0]
	v_pk_mul_f32 v[36:37], v[132:133], v[138:139] op_sel_hi:[1,0]
	s_waitcnt lgkmcnt(0)
	v_mfma_f32_16x16x32_bf16 v[64:67], v[68:71], v[76:79], v[64:67]
	ds_read_b128 v[68:71], v201 offset:43520
	s_lshl_b32 s70, s84, 9
	v_lshlrev_b32_e32 v138, 1, v136
	s_waitcnt lgkmcnt(0)
	v_mfma_f32_16x16x32_bf16 v[60:63], v[68:71], v[76:79], v[60:63]
	ds_read_b128 v[228:231], v201 offset:47872
	ds_read_b128 v[232:235], v201 offset:52224
	ds_read_b128 v[236:239], v201 offset:56576
	ds_read_b128 v[240:243], v201 offset:60928
	ds_read_b128 v[246:249], v201 offset:65280
	s_waitcnt lgkmcnt(4)
	v_mfma_f32_16x16x32_bf16 v[56:59], v[228:231], v[76:79], v[56:59]
	ds_read_b128 v[68:71], v212
	s_waitcnt lgkmcnt(4)
	v_mfma_f32_16x16x32_bf16 v[52:55], v[232:235], v[76:79], v[52:55]
	s_waitcnt lgkmcnt(3)
	v_mfma_f32_16x16x32_bf16 v[48:51], v[236:239], v[76:79], v[48:51]
	s_waitcnt lgkmcnt(2)
	v_mfma_f32_16x16x32_bf16 v[44:47], v[240:243], v[76:79], v[44:47]
	s_waitcnt lgkmcnt(1)
	v_mfma_f32_16x16x32_bf16 v[40:43], v[246:249], v[76:79], v[40:43]
	s_waitcnt lgkmcnt(0)
	v_mfma_f32_16x16x32_bf16 v[36:39], v[68:71], v[76:79], v[36:39]
	ds_read_b128 v[84:87], v200 offset:64
	ds_read_b128 v[68:71], v201 offset:64
	ds_read_b128 v[100:103], v201 offset:17472
	ds_read_b128 v[76:79], v201 offset:4416
	s_waitcnt lgkmcnt(1)
	v_mfma_f32_16x16x32_bf16 v[100:103], v[100:103], v[84:87], v[108:111]
	s_nop 2
	ds_read_b128 v[108:111], v201 offset:21824
	ds_read_b128 v[96:99], v201 offset:13120
	s_waitcnt lgkmcnt(1)
	v_mfma_f32_16x16x32_bf16 v[104:107], v[108:111], v[84:87], v[104:107]
	ds_read_b128 v[108:111], v201 offset:26176
	s_waitcnt lgkmcnt(0)
	v_mfma_f32_16x16x32_bf16 v[92:95], v[108:111], v[84:87], v[92:95]
	ds_read_b128 v[108:111], v201 offset:30528
	s_waitcnt lgkmcnt(0)
	v_mfma_f32_16x16x32_bf16 v[80:83], v[108:111], v[84:87], v[80:83]
	ds_read_b128 v[108:111], v201 offset:34880
	v_mfma_f32_16x16x32_bf16 v[68:71], v[68:71], v[84:87], v[88:91]
	s_nop 2
	ds_read_b128 v[88:91], v201 offset:8768
	s_waitcnt lgkmcnt(1)
	v_mfma_f32_16x16x32_bf16 v[72:75], v[108:111], v[84:87], v[72:75]
	ds_read_b128 v[228:231], v201 offset:39232
	ds_read_b128 v[232:235], v201 offset:43584
	ds_read_b128 v[236:239], v201 offset:47936
	ds_read_b128 v[240:243], v201 offset:52288
	ds_read_b128 v[246:249], v201 offset:56640
	ds_read_b128 v[250:253], v201 offset:60992
	s_waitcnt lgkmcnt(5)
; #define LAS __attribute__((address_space(3)))
; __device__ __forceinline__ void mout_phase(const Params& p, LAS unsigned char* lds) {
;     ...
;         for (int kk = 0; kk < 4; ++kk) { const bf16x8 sf = *(const LAS bf16x8*)(sb + j * 136 + kk * 32 + fq * 8);
; #pragma unroll
;             for (int nb = 0; nb < 17; ++nb) { const bf16x8 vf = *(const LAS bf16x8*)(T + (nb * 16 + fr) * 136 + kk * 32 + fq * 8);
;                 acc[nb] = __builtin_amdgcn_mfma_f32_16x16x32_bf16(vf, sf, acc[nb], 0, 0, 0); } }
;         const float nq = __shfl(acc[16][0], fr);
;         const float inv = 1.f / fmaxf(fabsf(nq), einv);
;         bf16_t* hd = (bf16_t*)(p.ws + WS_HDIR) + (size_t)(r0 + j) * 1024 + h * 256;
	v_mfma_f32_16x16x32_bf16 v[64:67], v[228:231], v[84:87], v[64:67]
	ds_read_b128 v[108:111], v201 offset:65344
	s_waitcnt lgkmcnt(5)
	v_mfma_f32_16x16x32_bf16 v[60:63], v[232:235], v[84:87], v[60:63]
	s_waitcnt lgkmcnt(4)
	v_mfma_f32_16x16x32_bf16 v[56:59], v[236:239], v[84:87], v[56:59]
	s_waitcnt lgkmcnt(3)
	v_mfma_f32_16x16x32_bf16 v[52:55], v[240:243], v[84:87], v[52:55]
	s_waitcnt lgkmcnt(2)
	v_mfma_f32_16x16x32_bf16 v[48:51], v[246:249], v[84:87], v[48:51]
	s_waitcnt lgkmcnt(1)
	v_mfma_f32_16x16x32_bf16 v[44:47], v[250:253], v[84:87], v[44:47]
	s_waitcnt lgkmcnt(0)
	v_mfma_f32_16x16x32_bf16 v[40:43], v[108:111], v[84:87], v[40:43]
	ds_read_b128 v[108:111], v212 offset:64
	v_mfma_f32_16x16x32_bf16 v[76:79], v[76:79], v[84:87], v[120:123]
	v_mfma_f32_16x16x32_bf16 v[88:91], v[88:91], v[84:87], v[116:119]
	v_mfma_f32_16x16x32_bf16 v[96:99], v[96:99], v[84:87], v[112:115]
	s_waitcnt lgkmcnt(0)
	v_mfma_f32_16x16x32_bf16 v[36:39], v[108:111], v[84:87], v[36:39]
	ds_read_b128 v[84:87], v200 offset:128
	ds_read_b128 v[108:111], v201 offset:128
	s_waitcnt lgkmcnt(0)
	v_mfma_f32_16x16x32_bf16 v[108:111], v[108:111], v[84:87], v[68:71]
	s_nop 2
	ds_read_b128 v[228:231], v201 offset:4480
	ds_read_b128 v[232:235], v201 offset:8832
	ds_read_b128 v[236:239], v201 offset:13184
	ds_read_b128 v[240:243], v201 offset:17536
	ds_read_b128 v[246:249], v201 offset:21888
	ds_read_b128 v[250:253], v201 offset:26240
	s_waitcnt lgkmcnt(5)
	v_mfma_f32_16x16x32_bf16 v[76:79], v[228:231], v[84:87], v[76:79]
	ds_read_b128 v[228:231], v201 offset:30592
	s_waitcnt lgkmcnt(5)
	v_mfma_f32_16x16x32_bf16 v[88:91], v[232:235], v[84:87], v[88:91]
	ds_read_b128 v[232:235], v201 offset:34944
	s_waitcnt lgkmcnt(5)
	v_mfma_f32_16x16x32_bf16 v[96:99], v[236:239], v[84:87], v[96:99]
	ds_read_b128 v[68:71], v201 offset:39296
	s_waitcnt lgkmcnt(5)
	v_mfma_f32_16x16x32_bf16 v[112:115], v[240:243], v[84:87], v[100:103]
	s_waitcnt lgkmcnt(4)
	v_mfma_f32_16x16x32_bf16 v[104:107], v[246:249], v[84:87], v[104:107]
	s_waitcnt lgkmcnt(3)
	v_mfma_f32_16x16x32_bf16 v[116:119], v[250:253], v[84:87], v[92:95]
	s_waitcnt lgkmcnt(2)
	v_mfma_f32_16x16x32_bf16 v[80:83], v[228:231], v[84:87], v[80:83]
	s_waitcnt lgkmcnt(1)
	v_mfma_f32_16x16x32_bf16 v[72:75], v[232:235], v[84:87], v[72:75]
	s_waitcnt lgkmcnt(0)
	v_mfma_f32_16x16x32_bf16 v[120:123], v[68:71], v[84:87], v[64:67]
	s_nop 2
	ds_read_b128 v[64:67], v201 offset:43648
	s_waitcnt lgkmcnt(0)
	v_mfma_f32_16x16x32_bf16 v[68:71], v[64:67], v[84:87], v[60:63]
	s_nop 2
	ds_read_b128 v[60:63], v201 offset:48000
	s_waitcnt lgkmcnt(0)
	v_mfma_f32_16x16x32_bf16 v[64:67], v[60:63], v[84:87], v[56:59]
	s_nop 2
	ds_read_b128 v[56:59], v201 offset:52352
	s_waitcnt lgkmcnt(0)
	v_mfma_f32_16x16x32_bf16 v[60:63], v[56:59], v[84:87], v[52:55]
	s_nop 2
	ds_read_b128 v[52:55], v201 offset:56704
	s_waitcnt lgkmcnt(0)
	v_mfma_f32_16x16x32_bf16 v[52:55], v[52:55], v[84:87], v[48:51]
	s_nop 2
	ds_read_b128 v[48:51], v201 offset:61056
	s_waitcnt lgkmcnt(0)
	v_mfma_f32_16x16x32_bf16 v[48:51], v[48:51], v[84:87], v[44:47]
	s_nop 2
	ds_read_b128 v[44:47], v201 offset:65408
	s_waitcnt lgkmcnt(0)
	v_mfma_f32_16x16x32_bf16 v[44:47], v[44:47], v[84:87], v[40:43]
	s_nop 2
	ds_read_b128 v[40:43], v212 offset:128
	s_waitcnt lgkmcnt(0)
	v_mfma_f32_16x16x32_bf16 v[100:103], v[40:43], v[84:87], v[36:39]
	ds_read_b128 v[124:127], v200 offset:192
	s_nop 1
	ds_read_b128 v[36:39], v201 offset:192
	ds_read_b128 v[40:43], v201 offset:4544
	ds_read_b128 v[56:59], v201 offset:8896
	s_waitcnt lgkmcnt(1)
	v_mfma_f32_16x16x32_bf16 v[40:43], v[40:43], v[124:127], v[76:79]
	s_nop 2
	ds_read_b128 v[76:79], v201 offset:13248
	ds_read_b128 v[84:87], v201 offset:17600
	s_waitcnt lgkmcnt(1)
	v_mfma_f32_16x16x32_bf16 v[76:79], v[76:79], v[124:127], v[96:99]
	s_waitcnt lgkmcnt(0)
	v_mfma_f32_16x16x32_bf16 v[96:99], v[84:87], v[124:127], v[112:115]
	ds_read_b128 v[84:87], v201 offset:21952
	s_waitcnt lgkmcnt(0)
	v_mfma_f32_16x16x32_bf16 v[92:95], v[84:87], v[124:127], v[104:107]
	ds_read_b128 v[84:87], v201 offset:26304
	s_nop 1
	ds_read_b128 v[104:107], v201 offset:43712
	v_mfma_f32_16x16x32_bf16 v[56:59], v[56:59], v[124:127], v[88:91]
	s_waitcnt lgkmcnt(1)
	v_mfma_f32_16x16x32_bf16 v[88:91], v[84:87], v[124:127], v[116:119]
	ds_read_b128 v[84:87], v201 offset:30656
	s_waitcnt lgkmcnt(0)
	v_mfma_f32_16x16x32_bf16 v[84:87], v[84:87], v[124:127], v[80:83]
	s_nop 2
	ds_read_b128 v[80:83], v201 offset:35008
	s_waitcnt lgkmcnt(0)
	v_mfma_f32_16x16x32_bf16 v[80:83], v[80:83], v[124:127], v[72:75]
	s_nop 2
	ds_read_b128 v[72:75], v201 offset:39360
	v_mfma_f32_16x16x32_bf16 v[68:71], v[104:107], v[124:127], v[68:71]
	ds_read_b128 v[228:231], v201 offset:48064
	ds_read_b128 v[232:235], v201 offset:52416
	ds_read_b128 v[236:239], v201 offset:56768
	ds_read_b128 v[240:243], v201 offset:61120
	ds_read_b128 v[246:249], v201 offset:65472
	s_waitcnt lgkmcnt(4)
	v_mfma_f32_16x16x32_bf16 v[64:67], v[228:231], v[124:127], v[64:67]
	ds_read_b128 v[104:107], v212 offset:192
	s_waitcnt lgkmcnt(4)
	v_mfma_f32_16x16x32_bf16 v[60:63], v[232:235], v[124:127], v[60:63]
	s_waitcnt lgkmcnt(3)
	v_mfma_f32_16x16x32_bf16 v[52:55], v[236:239], v[124:127], v[52:55]
	s_waitcnt lgkmcnt(2)
	v_mfma_f32_16x16x32_bf16 v[48:51], v[240:243], v[124:127], v[48:51]
	s_waitcnt lgkmcnt(1)
	v_mfma_f32_16x16x32_bf16 v[44:47], v[246:249], v[124:127], v[44:47]
	s_waitcnt lgkmcnt(0)
	v_mfma_f32_16x16x32_bf16 v[100:103], v[104:107], v[124:127], v[100:103]
	v_lshl_add_u32 v106, s85, 7, v194
	s_nop 6
	v_and_or_b32 v101, v224, 64, v147
	v_lshlrev_b32_e32 v101, 2, v101
	ds_bpermute_b32 v100, v101, v100
	v_max_f32_e32 v101, v153, v153
	v_ashrrev_i32_e32 v107, 31, v106
	v_mfma_f32_16x16x32_bf16 v[36:39], v[36:39], v[124:127], v[108:111]
	s_waitcnt lgkmcnt(0)
	v_max_f32_e64 v100, |v100|, |v100|
	v_max_f32_e32 v100, v100, v101
	v_div_scale_f32 v101, s[80:81], v100, v100, 1.0
	v_rcp_f32_e32 v102, v101
	v_mfma_f32_16x16x32_bf16 v[72:75], v[72:75], v[124:127], v[120:123]
	s_mov_b64 s[80:81], -1
	v_fma_f32 v103, -v101, v102, 1.0
	v_fmac_f32_e32 v102, v103, v102
	v_div_scale_f32 v103, vcc, 1.0, v100, 1.0
	v_mul_f32_e32 v104, v103, v102
	v_fma_f32 v105, -v101, v104, v103
	v_fmac_f32_e32 v104, v105, v102
	v_fma_f32 v101, -v101, v104, v103
	v_div_fmas_f32 v101, v101, v102, v104
	v_lshlrev_b64 v[102:103], 11, v[106:107]
	v_lshl_add_u64 v[102:103], s[2:3], 0, v[102:103]
	v_lshl_add_u64 v[102:103], v[102:103], 0, s[70:71]
	v_div_fixup_f32 v100, v101, v100, 1.0
	v_lshl_add_u64 v[102:103], v[102:103], 0, v[138:139]
	s_and_b64 vcc, exec, s[66:67]
	s_cbranch_vccnz .LBB0_1512
; __device__ __forceinline__ float bflo(unsigned u) { return __uint_as_float(u << 16); }
; __device__ __forceinline__ float bfhi(unsigned u) { return __uint_as_float(u & 0xffff0000u); }
; __device__ __forceinline__ void mout_phase(const Params& p, LAS unsigned char* lds) {
;     ...
;             float ss = 0.f;
; #pragma unroll
;             for (int nb = 0; nb < 16; ++nb) { const u32x2 hv = *(const u32x2*)(hd + nb * 16 + 4 * fq);
;                 acc[nb][0] = acc[nb][0] * inv + bflo(hv.x); acc[nb][1] = acc[nb][1] * inv + bfhi(hv.x); acc[nb][2] = acc[nb][2] * inv + bflo(hv.y); acc[nb][3] = acc[nb][3] * inv + bfhi(hv.y);
;                 ss += acc[nb][0] * acc[nb][0] + acc[nb][1] * acc[nb][1] + acc[nb][2] * acc[nb][2] + acc[nb][3] * acc[nb][3]; }
;             ss += __shfl_xor(ss, 16); ss += __shfl_xor(ss, 32);
	global_load_dwordx2 v[104:105], v[102:103], off
	global_load_dwordx2 v[110:111], v[102:103], off offset:32
	global_load_dwordx2 v[112:113], v[102:103], off offset:64
	global_load_dwordx2 v[114:115], v[102:103], off offset:96
	global_load_dwordx2 v[116:117], v[102:103], off offset:128
	global_load_dwordx2 v[118:119], v[102:103], off offset:160
	global_load_dwordx2 v[120:121], v[102:103], off offset:192
	global_load_dwordx2 v[122:123], v[102:103], off offset:224
	global_load_dwordx2 v[124:125], v[102:103], off offset:256
	global_load_dwordx2 v[130:131], v[102:103], off offset:288
	global_load_dwordx2 v[132:133], v[102:103], off offset:320
	global_load_dwordx2 v[134:135], v[102:103], off offset:352
	v_mov_b32_e32 v213, v244
	v_readlane_b32 s36, v255, 48
	v_lshlrev_b64 v[108:109], 10, v[106:107]
	v_readlane_b32 s37, v255, 49
	s_lshl_b32 s80, s84, 8
	v_lshlrev_b64 v[106:107], 12, v[106:107]
	v_lshl_add_u64 v[108:109], v[108:109], 1, s[36:37]
	v_readlane_b32 s36, v255, 50
	v_readlane_b32 s37, v255, 51
	s_lshl_b32 s70, s80, 1
	v_lshl_add_u64 v[108:109], v[108:109], 0, s[70:71]
	v_lshl_add_u64 v[106:107], s[36:37], 0, v[106:107]
	v_lshl_add_u64 v[108:109], v[108:109], 0, v[138:139]
	v_xor_b32_e32 v225, 16, v224
	s_waitcnt vmcnt(11)
	v_and_b32_e32 v163, 0xffff0000, v104
	s_waitcnt vmcnt(10)
	v_and_b32_e32 v171, 0xffff0000, v110
	v_lshlrev_b32_e32 v161, 16, v104
	v_lshlrev_b32_e32 v169, 16, v110
	s_waitcnt vmcnt(9)
	v_and_b32_e32 v236, 0xffff0000, v112
	v_fmac_f32_e32 v163, v37, v100
	v_fmac_f32_e32 v171, v41, v100
	v_lshlrev_b32_e32 v165, 16, v105
	v_and_b32_e32 v167, 0xffff0000, v105
	v_lshlrev_b32_e32 v173, 16, v111
	v_lshlrev_b32_e32 v177, 16, v112
	s_waitcnt vmcnt(8)
	v_and_b32_e32 v240, 0xffff0000, v114
	v_fmac_f32_e32 v161, v36, v100
	v_fmac_f32_e32 v169, v40, v100
	v_fmac_f32_e32 v236, v57, v100
	v_mul_f32_e32 v104, v163, v163
	v_mul_f32_e32 v105, v171, v171
	v_and_b32_e32 v175, 0xffff0000, v111
	v_lshlrev_b32_e32 v237, 16, v113
	v_lshlrev_b32_e32 v239, 16, v114
	s_waitcnt vmcnt(7)
	v_and_b32_e32 v244, 0xffff0000, v116
	v_fmac_f32_e32 v165, v38, v100
	v_fmac_f32_e32 v173, v42, v100
	v_fmac_f32_e32 v177, v56, v100
	v_fmac_f32_e32 v240, v77, v100
	v_mul_f32_e32 v110, v236, v236
	v_fmac_f32_e32 v104, v161, v161
	v_fmac_f32_e32 v105, v169, v169
	v_and_b32_e32 v238, 0xffff0000, v113
	v_lshlrev_b32_e32 v241, 16, v115
	v_lshlrev_b32_e32 v243, 16, v116
	s_waitcnt vmcnt(6)
	v_and_b32_e32 v155, 0xffff0000, v118
	v_fmac_f32_e32 v167, v39, v100
	v_fmac_f32_e32 v175, v43, v100
	v_fmac_f32_e32 v237, v58, v100
	v_fmac_f32_e32 v239, v76, v100
	v_fmac_f32_e32 v244, v97, v100
	v_mul_f32_e32 v111, v240, v240
	v_fmac_f32_e32 v110, v177, v177
	v_fmac_f32_e32 v104, v165, v165
	v_fmac_f32_e32 v105, v173, v173
	v_and_b32_e32 v242, 0xffff0000, v115
	v_lshlrev_b32_e32 v245, 16, v117
	v_lshlrev_b32_e32 v159, 16, v118
	v_fmac_f32_e32 v238, v59, v100
	v_fmac_f32_e32 v241, v78, v100
	v_fmac_f32_e32 v243, v96, v100
	v_fmac_f32_e32 v155, v93, v100
	v_mul_f32_e32 v112, v244, v244
	v_fmac_f32_e32 v111, v239, v239
	v_fmac_f32_e32 v110, v237, v237
	v_fmac_f32_e32 v104, v167, v167
	v_fmac_f32_e32 v105, v175, v175
	v_and_b32_e32 v246, 0xffff0000, v117
	v_lshlrev_b32_e32 v153, 16, v119
	v_fmac_f32_e32 v242, v79, v100
	v_fmac_f32_e32 v245, v98, v100
	v_fmac_f32_e32 v159, v92, v100
	v_mul_f32_e32 v113, v155, v155
	v_fmac_f32_e32 v112, v243, v243
	v_fmac_f32_e32 v111, v241, v241
	v_fmac_f32_e32 v110, v238, v238
	v_add_f32_e32 v104, v104, v105
	v_and_b32_e32 v101, 0xffff0000, v119
	v_fmac_f32_e32 v246, v99, v100
	v_fmac_f32_e32 v153, v94, v100
	v_fmac_f32_e32 v113, v159, v159
	v_fmac_f32_e32 v112, v245, v245
	v_fmac_f32_e32 v111, v242, v242
	v_add_f32_e32 v104, v104, v110
	v_fmac_f32_e32 v101, v95, v100
	v_fmac_f32_e32 v113, v153, v153
	v_fmac_f32_e32 v112, v246, v246
	v_add_f32_e32 v104, v104, v111
	v_fmac_f32_e32 v113, v101, v101
	v_add_f32_e32 v104, v104, v112
	v_add_f32_e32 v104, v104, v113
	global_load_dwordx2 v[110:111], v[102:103], off offset:384
	global_load_dwordx2 v[112:113], v[102:103], off offset:416
	global_load_dwordx2 v[116:117], v[102:103], off offset:448
	global_load_dwordx2 v[230:231], v[102:103], off offset:480
	s_waitcnt vmcnt(9)
	v_and_b32_e32 v248, 0xffff0000, v120
	v_lshlrev_b32_e32 v247, 16, v120
	v_fmac_f32_e32 v248, v89, v100
	v_fmac_f32_e32 v247, v88, v100
	v_lshlrev_b32_e32 v249, 16, v121
	v_mul_f32_e32 v105, v248, v248
	v_fmac_f32_e32 v249, v90, v100
	v_and_b32_e32 v250, 0xffff0000, v121
	v_fmac_f32_e32 v105, v247, v247
	v_fmac_f32_e32 v250, v91, v100
	v_fmac_f32_e32 v105, v249, v249
	s_waitcnt vmcnt(8)
	v_and_b32_e32 v252, 0xffff0000, v122
	v_fmac_f32_e32 v105, v250, v250
	v_lshlrev_b32_e32 v251, 16, v122
	v_fmac_f32_e32 v252, v85, v100
	v_add_f32_e32 v104, v104, v105
	v_fmac_f32_e32 v251, v84, v100
	v_lshlrev_b32_e32 v253, 16, v123
	v_mul_f32_e32 v105, v252, v252
	v_fmac_f32_e32 v253, v86, v100
	v_and_b32_e32 v141, 0xffff0000, v123
	v_fmac_f32_e32 v105, v251, v251
	v_fmac_f32_e32 v141, v87, v100
	v_fmac_f32_e32 v105, v253, v253
	v_fmac_f32_e32 v105, v141, v141
	v_add_f32_e32 v118, v104, v105
	v_mov_b32_e32 v104, v80
	v_mov_b32_e32 v105, v72
	s_waitcnt vmcnt(6)
	v_lshlrev_b32_e32 v115, 16, v130
	v_lshlrev_b32_e32 v114, 16, v124
	v_pk_fma_f32 v[126:127], v[104:105], v[100:101], v[114:115] op_sel_hi:[1,0,1]
	v_mov_b32_e32 v104, v81
	v_mov_b32_e32 v105, v73
	v_and_b32_e32 v115, 0xffff0000, v130
	v_and_b32_e32 v114, 0xffff0000, v124
	v_pk_fma_f32 v[128:129], v[104:105], v[100:101], v[114:115] op_sel_hi:[1,0,1]
	v_mov_b32_e32 v104, v82
	v_mov_b32_e32 v105, v74
	v_lshlrev_b32_e32 v115, 16, v131
	v_lshlrev_b32_e32 v114, 16, v125
	v_pk_fma_f32 v[180:181], v[104:105], v[100:101], v[114:115] op_sel_hi:[1,0,1]
	v_mov_b32_e32 v104, v83
	v_mov_b32_e32 v105, v75
	v_and_b32_e32 v115, 0xffff0000, v131
	v_and_b32_e32 v114, 0xffff0000, v125
	v_pk_fma_f32 v[182:183], v[104:105], v[100:101], v[114:115] op_sel_hi:[1,0,1]
	v_pk_mul_f32 v[104:105], v[128:129], v[128:129]
	s_waitcnt vmcnt(4)
; __device__ __forceinline__ float bflo(unsigned u) { return __uint_as_float(u << 16); }
; __device__ __forceinline__ float bfhi(unsigned u) { return __uint_as_float(u & 0xffff0000u); }
; __device__ __forceinline__ void mout_phase(const Params& p, LAS unsigned char* lds) {
;     ...
;             float ss = 0.f;
; #pragma unroll
;             for (int nb = 0; nb < 16; ++nb) { const u32x2 hv = *(const u32x2*)(hd + nb * 16 + 4 * fq);
;                 acc[nb][0] = acc[nb][0] * inv + bflo(hv.x); acc[nb][1] = acc[nb][1] * inv + bfhi(hv.x); acc[nb][2] = acc[nb][2] * inv + bflo(hv.y); acc[nb][3] = acc[nb][3] * inv + bfhi(hv.y);
;                 ss += acc[nb][0] * acc[nb][0] + acc[nb][1] * acc[nb][1] + acc[nb][2] * acc[nb][2] + acc[nb][3] * acc[nb][3]; }
;             ss += __shfl_xor(ss, 16); ss += __shfl_xor(ss, 32);
;             const float rstd = rsqrtf(ss * (1.f / 256.f) + 1e-6f);
;             const float* ng = p.in[15] + h * 256;
;             const bf16_t* og = (const bf16_t*)(p.ws + WS_O) + (size_t)(r0 + j) * 1024 + h * 256;
;             bf16_t* cat = (bf16_t*)(p.ws + WS_CAT) + (size_t)(r0 + j) * 2048 + h * 256;
; #pragma unroll
;             for (int nb = 0; nb < 16; ++nb) { const int dv = nb * 16 + 4 * fq; const f32x4 gn = *(const f32x4*)(ng + dv); const u32x2 ov = *(const u32x2*)(og + dv);
	v_lshlrev_b32_e32 v115, 16, v134
	v_pk_fma_f32 v[104:105], v[126:127], v[126:127], v[104:105]
	v_lshlrev_b32_e32 v114, 16, v132
	v_pk_fma_f32 v[104:105], v[180:181], v[180:181], v[104:105]
	global_load_dwordx2 v[232:233], v[108:109], off
	v_pk_fma_f32 v[104:105], v[182:183], v[182:183], v[104:105]
	s_waitcnt vmcnt(2)
	v_lshlrev_b32_e32 v234, 16, v117
	v_add_f32_e32 v104, v118, v104
	v_add_f32_e32 v130, v104, v105
	v_mov_b32_e32 v104, v68
	v_mov_b32_e32 v105, v64
	v_pk_fma_f32 v[118:119], v[104:105], v[100:101], v[114:115] op_sel_hi:[1,0,1]
	v_mov_b32_e32 v104, v69
	v_mov_b32_e32 v105, v65
	v_and_b32_e32 v115, 0xffff0000, v134
	v_and_b32_e32 v114, 0xffff0000, v132
	v_pk_fma_f32 v[120:121], v[104:105], v[100:101], v[114:115] op_sel_hi:[1,0,1]
	v_mov_b32_e32 v104, v70
	v_mov_b32_e32 v105, v66
	v_lshlrev_b32_e32 v115, 16, v135
	v_lshlrev_b32_e32 v114, 16, v133
	v_pk_fma_f32 v[122:123], v[104:105], v[100:101], v[114:115] op_sel_hi:[1,0,1]
	v_mov_b32_e32 v104, v71
	v_mov_b32_e32 v105, v67
	v_and_b32_e32 v115, 0xffff0000, v135
	v_and_b32_e32 v114, 0xffff0000, v133
	v_pk_fma_f32 v[124:125], v[104:105], v[100:101], v[114:115] op_sel_hi:[1,0,1]
	v_pk_mul_f32 v[104:105], v[120:121], v[120:121]
	v_lshlrev_b32_e32 v115, 16, v112
	v_pk_fma_f32 v[104:105], v[118:119], v[118:119], v[104:105]
	v_lshlrev_b32_e32 v114, 16, v110
	v_pk_fma_f32 v[104:105], v[122:123], v[122:123], v[104:105]
	v_and_b32_e32 v133, 0xffff0000, v112
	v_pk_fma_f32 v[104:105], v[124:125], v[124:125], v[104:105]
	v_and_b32_e32 v132, 0xffff0000, v110
	v_add_f32_e32 v104, v130, v104
	v_lshl_add_u64 v[130:131], v[106:107], 0, s[70:71]
	s_lshl_b32 s70, s80, 2
	v_lshl_add_u64 v[106:107], v[150:151], 0, s[70:71]
	global_load_dwordx4 v[226:229], v[106:107], off
	v_add_f32_e32 v157, v104, v105
	v_mov_b32_e32 v104, v60
	v_mov_b32_e32 v105, v52
	v_pk_fma_f32 v[104:105], v[104:105], v[100:101], v[114:115] op_sel_hi:[1,0,1]
	v_mov_b32_e32 v114, v61
	v_mov_b32_e32 v115, v53
	v_pk_fma_f32 v[132:133], v[114:115], v[100:101], v[132:133] op_sel_hi:[1,0,1]
	v_mov_b32_e32 v114, v62
	v_mov_b32_e32 v115, v54
	v_lshlrev_b32_e32 v135, 16, v113
	v_lshlrev_b32_e32 v134, 16, v111
	v_and_b32_e32 v112, 0xffff0000, v111
	v_pk_mul_f32 v[110:111], v[132:133], v[132:133]
	v_pk_fma_f32 v[134:135], v[114:115], v[100:101], v[134:135] op_sel_hi:[1,0,1]
	v_mov_b32_e32 v114, v63
	v_mov_b32_e32 v115, v55
	v_and_b32_e32 v113, 0xffff0000, v113
	v_pk_fma_f32 v[110:111], v[104:105], v[104:105], v[110:111]
	v_pk_fma_f32 v[178:179], v[114:115], v[100:101], v[112:113] op_sel_hi:[1,0,1]
	v_pk_fma_f32 v[110:111], v[134:135], v[134:135], v[110:111]
	s_waitcnt vmcnt(2)
	v_lshlrev_b32_e32 v113, 16, v230
	v_pk_fma_f32 v[110:111], v[178:179], v[178:179], v[110:111]
	v_lshlrev_b32_e32 v112, 16, v116
	v_add_f32_e32 v110, v157, v110
	v_add_f32_e32 v157, v110, v111
	v_mov_b32_e32 v110, v48
	v_mov_b32_e32 v111, v44
	v_pk_fma_f32 v[110:111], v[110:111], v[100:101], v[112:113] op_sel_hi:[1,0,1]
	v_mov_b32_e32 v112, v49
	v_mov_b32_e32 v113, v45
	v_and_b32_e32 v115, 0xffff0000, v230
	v_and_b32_e32 v114, 0xffff0000, v116
	v_pk_fma_f32 v[112:113], v[112:113], v[100:101], v[114:115] op_sel_hi:[1,0,1]
	v_mov_b32_e32 v114, v50
	v_mov_b32_e32 v115, v46
	v_lshlrev_b32_e32 v235, 16, v231
	v_pk_fma_f32 v[114:115], v[114:115], v[100:101], v[234:235] op_sel_hi:[1,0,1]
	v_mov_b32_e32 v234, v51
	v_mov_b32_e32 v235, v47
	v_and_b32_e32 v231, 0xffff0000, v231
	v_and_b32_e32 v230, 0xffff0000, v117
	v_pk_fma_f32 v[116:117], v[234:235], v[100:101], v[230:231] op_sel_hi:[1,0,1]
	v_pk_mul_f32 v[230:231], v[112:113], v[112:113]
	s_mov_b32 s70, 0x800000
	v_pk_fma_f32 v[230:231], v[110:111], v[110:111], v[230:231]
	v_lshl_add_u64 v[130:131], v[130:131], 0, v[138:139]
	v_pk_fma_f32 v[230:231], v[114:115], v[114:115], v[230:231]
	s_mov_b64 s[80:81], 0
	v_pk_fma_f32 v[230:231], v[116:117], v[116:117], v[230:231]
	s_nop 0
	v_add_f32_e32 v157, v157, v230
	v_and_b32_e32 v230, 64, v224
	v_add_u32_e32 v230, 64, v230
	v_cmp_lt_i32_e32 vcc, v225, v230
	v_add_f32_e32 v157, v157, v231
	s_nop 0
	v_cndmask_b32_e32 v225, v224, v225, vcc
	v_lshlrev_b32_e32 v225, 2, v225
	ds_bpermute_b32 v225, v225, v157
	s_waitcnt lgkmcnt(0)
	v_add_f32_e32 v157, v157, v225
	v_xor_b32_e32 v225, 32, v224
	v_cmp_lt_i32_e32 vcc, v225, v230
	s_nop 1
	v_cndmask_b32_e32 v224, v224, v225, vcc
	v_lshlrev_b32_e32 v224, 2, v224
	ds_bpermute_b32 v224, v224, v157
	s_waitcnt lgkmcnt(0)
	v_add_f32_e32 v157, v157, v224
	v_mov_b32_e32 v224, 0x358637bd
	v_fmamk_f32 v157, v157, 0x3b800000, v224
	v_mul_f32_e32 v224, 0x4b800000, v157
	v_cmp_gt_f32_e32 vcc, s70, v157
	s_nop 1
	v_cndmask_b32_e32 v157, v157, v224, vcc
	v_rsq_f32_e32 v157, v157
	s_nop 0
	v_mul_f32_e32 v224, 0x45800000, v157
	v_cndmask_b32_e32 v157, v157, v224, vcc
	global_load_dwordx2 v[36:37], v[108:109], off offset:32
	global_load_dwordx2 v[38:39], v[108:109], off offset:64
	global_load_dwordx2 v[40:41], v[108:109], off offset:96
	global_load_dwordx2 v[42:43], v[108:109], off offset:128
	global_load_dwordx2 v[44:45], v[108:109], off offset:160
	global_load_dwordx2 v[46:47], v[108:109], off offset:192
	global_load_dwordx2 v[48:49], v[108:109], off offset:224
	global_load_dwordx2 v[50:51], v[108:109], off offset:256
	global_load_dwordx2 v[52:53], v[108:109], off offset:288
	global_load_dwordx2 v[54:55], v[108:109], off offset:320
	global_load_dwordx2 v[56:57], v[108:109], off offset:352
	global_load_dwordx2 v[58:59], v[108:109], off offset:384
	global_load_dwordx2 v[60:61], v[108:109], off offset:416
	global_load_dwordx2 v[62:63], v[108:109], off offset:448
	global_load_dwordx2 v[64:65], v[108:109], off offset:480
	global_load_dwordx4 v[68:71], v[106:107], off offset:64
	global_load_dwordx4 v[72:75], v[106:107], off offset:128
	global_load_dwordx4 v[76:79], v[106:107], off offset:192
	global_load_dwordx4 v[80:83], v[106:107], off offset:256
	global_load_dwordx4 v[84:87], v[106:107], off offset:320
	global_load_dwordx4 v[88:91], v[106:107], off offset:384
	global_load_dwordx4 v[92:95], v[106:107], off offset:448
	global_load_dwordx4 v[96:99], v[106:107], off offset:512
	s_waitcnt vmcnt(23)
; __device__ __forceinline__ unsigned cvt_pk_bf16(float lo, float hi) { unsigned r; asm volatile("v_cvt_pk_bf16_f32 %0, %1, %2" : "=v"(r) : "v"(lo), "v"(hi)); return r; }
; __device__ __forceinline__ float bflo(unsigned u) { return __uint_as_float(u << 16); }
; __device__ __forceinline__ float bfhi(unsigned u) { return __uint_as_float(u & 0xffff0000u); }
; __device__ __forceinline__ void mout_phase(const Params& p, LAS unsigned char* lds) {
;     ...
;             for (int nb = 0; nb < 16; ++nb) { const int dv = nb * 16 + 4 * fq; const f32x4 gn = *(const f32x4*)(ng + dv); const u32x2 ov = *(const u32x2*)(og + dv);
;                 u32x2 o; o.x = cvt_pk_bf16(acc[nb][0] * rstd * gn[0] * bflo(ov.x), acc[nb][1] * rstd * gn[1] * bfhi(ov.x));
;                 o.y = cvt_pk_bf16(acc[nb][2] * rstd * gn[2] * bflo(ov.y), acc[nb][3] * rstd * gn[3] * bfhi(ov.y));
;                 *(u32x2*)(cat + dv) = o;
;                 if ((nb & 3) == 3) asm volatile("" ::: "memory"); }
	v_mul_f32_e32 v161, v161, v157
	v_mul_f32_e32 v161, v161, v226
	v_lshlrev_b32_e32 v230, 16, v232
	v_mul_f32_e32 v161, v161, v230
	v_mul_f32_e32 v163, v163, v157
	v_mul_f32_e32 v163, v163, v227
	v_and_b32_e32 v230, 0xffff0000, v232
	v_mul_f32_e32 v163, v163, v230
	v_mul_f32_e32 v165, v165, v157
	v_mul_f32_e32 v165, v165, v228
	v_lshlrev_b32_e32 v230, 16, v233
	v_mul_f32_e32 v165, v165, v230
	v_mul_f32_e32 v167, v167, v157
	v_mul_f32_e32 v167, v167, v229
	v_and_b32_e32 v230, 0xffff0000, v233
	v_mul_f32_e32 v167, v167, v230
	v_cvt_pk_bf16_f32 v224, v161, v163
	v_cvt_pk_bf16_f32 v225, v165, v167
	global_store_dwordx2 v[130:131], v[224:225], off
	s_waitcnt vmcnt(8)
	v_mul_f32_e32 v169, v169, v157
	v_mul_f32_e32 v169, v169, v68
	v_lshlrev_b32_e32 v230, 16, v36
	v_mul_f32_e32 v169, v169, v230
	v_mul_f32_e32 v171, v171, v157
	v_mul_f32_e32 v171, v171, v69
	v_and_b32_e32 v230, 0xffff0000, v36
	v_mul_f32_e32 v171, v171, v230
	v_mul_f32_e32 v173, v173, v157
	v_mul_f32_e32 v173, v173, v70
	v_lshlrev_b32_e32 v230, 16, v37
	v_mul_f32_e32 v173, v173, v230
	v_mul_f32_e32 v175, v175, v157
	v_mul_f32_e32 v175, v175, v71
	v_and_b32_e32 v230, 0xffff0000, v37
	v_mul_f32_e32 v175, v175, v230
	v_cvt_pk_bf16_f32 v224, v169, v171
	v_cvt_pk_bf16_f32 v225, v173, v175
	global_store_dwordx2 v[130:131], v[224:225], off offset:32
	s_waitcnt vmcnt(8)
	v_mul_f32_e32 v177, v177, v157
	v_mul_f32_e32 v177, v177, v72
	v_lshlrev_b32_e32 v230, 16, v38
	v_mul_f32_e32 v177, v177, v230
	v_mul_f32_e32 v236, v236, v157
	v_mul_f32_e32 v236, v236, v73
	v_and_b32_e32 v230, 0xffff0000, v38
	v_mul_f32_e32 v236, v236, v230
	v_mul_f32_e32 v237, v237, v157
	v_mul_f32_e32 v237, v237, v74
	v_lshlrev_b32_e32 v230, 16, v39
	v_mul_f32_e32 v237, v237, v230
	v_mul_f32_e32 v238, v238, v157
	v_mul_f32_e32 v238, v238, v75
	v_and_b32_e32 v230, 0xffff0000, v39
	v_mul_f32_e32 v238, v238, v230
	v_cvt_pk_bf16_f32 v224, v177, v236
	v_cvt_pk_bf16_f32 v225, v237, v238
	global_store_dwordx2 v[130:131], v[224:225], off offset:64
	s_waitcnt vmcnt(8)
	v_mul_f32_e32 v239, v239, v157
	v_mul_f32_e32 v239, v239, v76
	v_lshlrev_b32_e32 v230, 16, v40
	v_mul_f32_e32 v239, v239, v230
	v_mul_f32_e32 v240, v240, v157
	v_mul_f32_e32 v240, v240, v77
	v_and_b32_e32 v230, 0xffff0000, v40
	v_mul_f32_e32 v240, v240, v230
	v_mul_f32_e32 v241, v241, v157
	v_mul_f32_e32 v241, v241, v78
	v_lshlrev_b32_e32 v230, 16, v41
	v_mul_f32_e32 v241, v241, v230
	v_mul_f32_e32 v242, v242, v157
	v_mul_f32_e32 v242, v242, v79
	v_and_b32_e32 v230, 0xffff0000, v41
	v_mul_f32_e32 v242, v242, v230
	v_cvt_pk_bf16_f32 v224, v239, v240
	v_cvt_pk_bf16_f32 v225, v241, v242
	global_store_dwordx2 v[130:131], v[224:225], off offset:96
	s_waitcnt vmcnt(8)
	v_mul_f32_e32 v243, v243, v157
	v_mul_f32_e32 v243, v243, v80
	v_lshlrev_b32_e32 v230, 16, v42
	v_mul_f32_e32 v243, v243, v230
	v_mul_f32_e32 v244, v244, v157
	v_mul_f32_e32 v244, v244, v81
	v_and_b32_e32 v230, 0xffff0000, v42
	v_mul_f32_e32 v244, v244, v230
	v_mul_f32_e32 v245, v245, v157
	v_mul_f32_e32 v245, v245, v82
	v_lshlrev_b32_e32 v230, 16, v43
	v_mul_f32_e32 v245, v245, v230
	v_mul_f32_e32 v246, v246, v157
	v_mul_f32_e32 v246, v246, v83
	v_and_b32_e32 v230, 0xffff0000, v43
	v_mul_f32_e32 v246, v246, v230
	v_cvt_pk_bf16_f32 v224, v243, v244
	v_cvt_pk_bf16_f32 v225, v245, v246
	global_store_dwordx2 v[130:131], v[224:225], off offset:128
	s_waitcnt vmcnt(8)
	v_mul_f32_e32 v159, v159, v157
	v_mul_f32_e32 v159, v159, v84
	v_lshlrev_b32_e32 v230, 16, v44
	v_mul_f32_e32 v159, v159, v230
	v_mul_f32_e32 v155, v155, v157
	v_mul_f32_e32 v155, v155, v85
	v_and_b32_e32 v230, 0xffff0000, v44
	v_mul_f32_e32 v155, v155, v230
	v_mul_f32_e32 v153, v153, v157
	v_mul_f32_e32 v153, v153, v86
	v_lshlrev_b32_e32 v230, 16, v45
	v_mul_f32_e32 v153, v153, v230
	v_mul_f32_e32 v101, v101, v157
	v_mul_f32_e32 v101, v101, v87
	v_and_b32_e32 v230, 0xffff0000, v45
	v_mul_f32_e32 v101, v101, v230
	v_cvt_pk_bf16_f32 v224, v159, v155
	v_cvt_pk_bf16_f32 v225, v153, v101
	global_store_dwordx2 v[130:131], v[224:225], off offset:160
	s_waitcnt vmcnt(8)
	v_mul_f32_e32 v247, v247, v157
	v_mul_f32_e32 v247, v247, v88
	v_lshlrev_b32_e32 v230, 16, v46
	v_mul_f32_e32 v247, v247, v230
	v_mul_f32_e32 v248, v248, v157
	v_mul_f32_e32 v248, v248, v89
	v_and_b32_e32 v230, 0xffff0000, v46
	v_mul_f32_e32 v248, v248, v230
	v_mul_f32_e32 v249, v249, v157
	v_mul_f32_e32 v249, v249, v90
	v_lshlrev_b32_e32 v230, 16, v47
	v_mul_f32_e32 v249, v249, v230
	v_mul_f32_e32 v250, v250, v157
	v_mul_f32_e32 v250, v250, v91
	v_and_b32_e32 v230, 0xffff0000, v47
	v_mul_f32_e32 v250, v250, v230
	v_cvt_pk_bf16_f32 v224, v247, v248
	v_cvt_pk_bf16_f32 v225, v249, v250
	global_store_dwordx2 v[130:131], v[224:225], off offset:192
	s_waitcnt vmcnt(8)
	v_mul_f32_e32 v251, v251, v157
	v_mul_f32_e32 v251, v251, v92
	v_lshlrev_b32_e32 v230, 16, v48
	v_mul_f32_e32 v251, v251, v230
	v_mul_f32_e32 v252, v252, v157
	v_mul_f32_e32 v252, v252, v93
	v_and_b32_e32 v230, 0xffff0000, v48
	v_mul_f32_e32 v252, v252, v230
	v_mul_f32_e32 v253, v253, v157
	v_mul_f32_e32 v253, v253, v94
	v_lshlrev_b32_e32 v230, 16, v49
	v_mul_f32_e32 v253, v253, v230
	v_mul_f32_e32 v141, v141, v157
	v_mul_f32_e32 v141, v141, v95
	v_and_b32_e32 v230, 0xffff0000, v49
	v_mul_f32_e32 v141, v141, v230
	v_cvt_pk_bf16_f32 v224, v251, v252
	v_cvt_pk_bf16_f32 v225, v253, v141
	global_store_dwordx2 v[130:131], v[224:225], off offset:224
	s_waitcnt vmcnt(8)
; __device__ __forceinline__ unsigned cvt_pk_bf16(float lo, float hi) { unsigned r; asm volatile("v_cvt_pk_bf16_f32 %0, %1, %2" : "=v"(r) : "v"(lo), "v"(hi)); return r; }
; __device__ __forceinline__ float bflo(unsigned u) { return __uint_as_float(u << 16); }
; __device__ __forceinline__ float bfhi(unsigned u) { return __uint_as_float(u & 0xffff0000u); }
; __device__ __forceinline__ void mout_phase(const Params& p, LAS unsigned char* lds) {
;     ...
;             for (int nb = 0; nb < 16; ++nb) { const int dv = nb * 16 + 4 * fq; const f32x4 gn = *(const f32x4*)(ng + dv); const u32x2 ov = *(const u32x2*)(og + dv);
;                 u32x2 o; o.x = cvt_pk_bf16(acc[nb][0] * rstd * gn[0] * bflo(ov.x), acc[nb][1] * rstd * gn[1] * bfhi(ov.x));
;                 o.y = cvt_pk_bf16(acc[nb][2] * rstd * gn[2] * bflo(ov.y), acc[nb][3] * rstd * gn[3] * bfhi(ov.y));
;                 *(u32x2*)(cat + dv) = o;
;                 if ((nb & 3) == 3) asm volatile("" ::: "memory"); }
	v_mul_f32_e32 v126, v126, v157
	v_mul_f32_e32 v126, v126, v96
	v_lshlrev_b32_e32 v230, 16, v50
	v_mul_f32_e32 v126, v126, v230
	v_mul_f32_e32 v128, v128, v157
	v_mul_f32_e32 v128, v128, v97
	v_and_b32_e32 v230, 0xffff0000, v50
	v_mul_f32_e32 v128, v128, v230
	v_mul_f32_e32 v180, v180, v157
	v_mul_f32_e32 v180, v180, v98
	v_lshlrev_b32_e32 v230, 16, v51
	v_mul_f32_e32 v180, v180, v230
	v_mul_f32_e32 v182, v182, v157
	v_mul_f32_e32 v182, v182, v99
	v_and_b32_e32 v230, 0xffff0000, v51
	v_mul_f32_e32 v182, v182, v230
	v_cvt_pk_bf16_f32 v224, v126, v128
	v_cvt_pk_bf16_f32 v225, v180, v182
	global_store_dwordx2 v[130:131], v[224:225], off offset:256
	global_load_dwordx4 v[68:71], v[106:107], off offset:576
	global_load_dwordx4 v[72:75], v[106:107], off offset:640
	global_load_dwordx4 v[76:79], v[106:107], off offset:704
	global_load_dwordx4 v[80:83], v[106:107], off offset:768
	global_load_dwordx4 v[84:87], v[106:107], off offset:832
	global_load_dwordx4 v[88:91], v[106:107], off offset:896
	global_load_dwordx4 v[92:95], v[106:107], off offset:960
	s_waitcnt vmcnt(6)
	v_mul_f32_e32 v127, v127, v157
	v_mul_f32_e32 v127, v127, v68
	v_lshlrev_b32_e32 v230, 16, v52
	v_mul_f32_e32 v127, v127, v230
	v_mul_f32_e32 v129, v129, v157
	v_mul_f32_e32 v129, v129, v69
	v_and_b32_e32 v230, 0xffff0000, v52
	v_mul_f32_e32 v129, v129, v230
	v_mul_f32_e32 v181, v181, v157
	v_mul_f32_e32 v181, v181, v70
	v_lshlrev_b32_e32 v230, 16, v53
	v_mul_f32_e32 v181, v181, v230
	v_mul_f32_e32 v183, v183, v157
	v_mul_f32_e32 v183, v183, v71
	v_and_b32_e32 v230, 0xffff0000, v53
	v_mul_f32_e32 v183, v183, v230
	v_cvt_pk_bf16_f32 v224, v127, v129
	v_cvt_pk_bf16_f32 v225, v181, v183
	global_store_dwordx2 v[130:131], v[224:225], off offset:288
	s_waitcnt vmcnt(6)
	v_mul_f32_e32 v118, v118, v157
	v_mul_f32_e32 v118, v118, v72
	v_lshlrev_b32_e32 v230, 16, v54
	v_mul_f32_e32 v118, v118, v230
	v_mul_f32_e32 v120, v120, v157
	v_mul_f32_e32 v120, v120, v73
	v_and_b32_e32 v230, 0xffff0000, v54
	v_mul_f32_e32 v120, v120, v230
	v_mul_f32_e32 v122, v122, v157
	v_mul_f32_e32 v122, v122, v74
	v_lshlrev_b32_e32 v230, 16, v55
	v_mul_f32_e32 v122, v122, v230
	v_mul_f32_e32 v124, v124, v157
	v_mul_f32_e32 v124, v124, v75
	v_and_b32_e32 v230, 0xffff0000, v55
	v_mul_f32_e32 v124, v124, v230
	v_cvt_pk_bf16_f32 v224, v118, v120
	v_cvt_pk_bf16_f32 v225, v122, v124
	global_store_dwordx2 v[130:131], v[224:225], off offset:320
	s_waitcnt vmcnt(6)
	v_mul_f32_e32 v119, v119, v157
	v_mul_f32_e32 v119, v119, v76
	v_lshlrev_b32_e32 v230, 16, v56
	v_mul_f32_e32 v119, v119, v230
	v_mul_f32_e32 v121, v121, v157
	v_mul_f32_e32 v121, v121, v77
	v_and_b32_e32 v230, 0xffff0000, v56
	v_mul_f32_e32 v121, v121, v230
	v_mul_f32_e32 v123, v123, v157
	v_mul_f32_e32 v123, v123, v78
	v_lshlrev_b32_e32 v230, 16, v57
	v_mul_f32_e32 v123, v123, v230
	v_mul_f32_e32 v125, v125, v157
	v_mul_f32_e32 v125, v125, v79
	v_and_b32_e32 v230, 0xffff0000, v57
	v_mul_f32_e32 v125, v125, v230
	v_cvt_pk_bf16_f32 v224, v119, v121
	v_cvt_pk_bf16_f32 v225, v123, v125
	global_store_dwordx2 v[130:131], v[224:225], off offset:352
	s_waitcnt vmcnt(6)
	v_mul_f32_e32 v104, v104, v157
	v_mul_f32_e32 v104, v104, v80
	v_lshlrev_b32_e32 v230, 16, v58
	v_mul_f32_e32 v104, v104, v230
	v_mul_f32_e32 v132, v132, v157
	v_mul_f32_e32 v132, v132, v81
	v_and_b32_e32 v230, 0xffff0000, v58
	v_mul_f32_e32 v132, v132, v230
	v_mul_f32_e32 v134, v134, v157
	v_mul_f32_e32 v134, v134, v82
	v_lshlrev_b32_e32 v230, 16, v59
	v_mul_f32_e32 v134, v134, v230
	v_mul_f32_e32 v178, v178, v157
	v_mul_f32_e32 v178, v178, v83
	v_and_b32_e32 v230, 0xffff0000, v59
	v_mul_f32_e32 v178, v178, v230
	v_cvt_pk_bf16_f32 v224, v104, v132
	v_cvt_pk_bf16_f32 v225, v134, v178
	global_store_dwordx2 v[130:131], v[224:225], off offset:384
	s_waitcnt vmcnt(6)
	v_mul_f32_e32 v105, v105, v157
	v_mul_f32_e32 v105, v105, v84
	v_lshlrev_b32_e32 v230, 16, v60
	v_mul_f32_e32 v105, v105, v230
	v_mul_f32_e32 v133, v133, v157
	v_mul_f32_e32 v133, v133, v85
	v_and_b32_e32 v230, 0xffff0000, v60
	v_mul_f32_e32 v133, v133, v230
	v_mul_f32_e32 v135, v135, v157
	v_mul_f32_e32 v135, v135, v86
	v_lshlrev_b32_e32 v230, 16, v61
	v_mul_f32_e32 v135, v135, v230
	v_mul_f32_e32 v179, v179, v157
	v_mul_f32_e32 v179, v179, v87
	v_and_b32_e32 v230, 0xffff0000, v61
	v_mul_f32_e32 v179, v179, v230
	v_cvt_pk_bf16_f32 v224, v105, v133
	v_cvt_pk_bf16_f32 v225, v135, v179
	global_store_dwordx2 v[130:131], v[224:225], off offset:416
	s_waitcnt vmcnt(6)
	v_mul_f32_e32 v110, v110, v157
	v_mul_f32_e32 v110, v110, v88
	v_lshlrev_b32_e32 v230, 16, v62
	v_mul_f32_e32 v110, v110, v230
	v_mul_f32_e32 v112, v112, v157
	v_mul_f32_e32 v112, v112, v89
	v_and_b32_e32 v230, 0xffff0000, v62
	v_mul_f32_e32 v112, v112, v230
	v_mul_f32_e32 v114, v114, v157
	v_mul_f32_e32 v114, v114, v90
	v_lshlrev_b32_e32 v230, 16, v63
	v_mul_f32_e32 v114, v114, v230
	v_mul_f32_e32 v116, v116, v157
	v_mul_f32_e32 v116, v116, v91
	v_and_b32_e32 v230, 0xffff0000, v63
	v_mul_f32_e32 v116, v116, v230
	v_cvt_pk_bf16_f32 v224, v110, v112
	v_cvt_pk_bf16_f32 v225, v114, v116
	global_store_dwordx2 v[130:131], v[224:225], off offset:448
	s_waitcnt vmcnt(6)
	v_mul_f32_e32 v111, v111, v157
	v_mul_f32_e32 v111, v111, v92
	v_lshlrev_b32_e32 v230, 16, v64
	v_mul_f32_e32 v111, v111, v230
	v_mul_f32_e32 v113, v113, v157
	v_mul_f32_e32 v113, v113, v93
	v_and_b32_e32 v230, 0xffff0000, v64
	v_mul_f32_e32 v113, v113, v230
	v_mul_f32_e32 v115, v115, v157
	v_mul_f32_e32 v115, v115, v94
	v_lshlrev_b32_e32 v230, 16, v65
	v_mul_f32_e32 v115, v115, v230
	v_mul_f32_e32 v117, v117, v157
	v_mul_f32_e32 v117, v117, v95
	v_and_b32_e32 v230, 0xffff0000, v65
	v_mul_f32_e32 v117, v117, v230
	v_cvt_pk_bf16_f32 v224, v111, v113
	v_cvt_pk_bf16_f32 v225, v115, v117
	global_store_dwordx2 v[130:131], v[224:225], off offset:480
	v_mov_b32_e32 v244, v213
